# e3 plus GEMM K-loop handoff trim: first MFMA issued directly after the barrier (redundant lgkmcnt wait dropped, setprio moved behind it), barrier issued directly after the last MFMA
# speedup vs baseline: 1.0098x; 1.0098x over previous
.LBB0_414:
	s_add_i32 s79, s0, 2
	s_add_u32 s83, s52, 0x80
	s_addc_u32 s1, s53, 0
	s_add_i32 s91, 0, 0x10000
	s_cmp_eq_u32 s40, s0
	s_cselect_b32 s1, s7, s1
	s_cselect_b32 s0, s6, s83
	v_add_u32_e32 v140, s91, v144
	s_cselect_b32 s87, s39, s78
	s_cselect_b32 s86, s38, s75
	s_add_i32 s83, 0, 0x14000
	ds_read_b128 v[148:151], v140
	ds_read_b128 v[152:155], v140 offset:1024
	ds_read_b128 v[156:159], v140 offset:2048
	ds_read_b128 v[160:163], v140 offset:3072
	v_add_u32_e32 v140, s83, v144
	ds_read_b128 v[164:167], v140
	ds_read_b128 v[168:171], v140 offset:1024
	ds_read_b128 v[172:175], v140 offset:2048
	ds_read_b128 v[176:179], v140 offset:3072
	v_lshl_add_u64 v[142:143], s[52:53], 0, v[136:137]
	s_add_i32 m0, s23, 0xc000
	ds_read_b128 v[180:183], v146
	ds_read_b128 v[184:187], v146 offset:1024
	ds_read_b128 v[188:191], v146 offset:2048
	ds_read_b128 v[192:195], v146 offset:3072
	ds_read_b128 v[196:199], v146 offset:4096
	ds_read_b128 v[200:203], v146 offset:5120
	ds_read_b128 v[204:207], v146 offset:6144
	ds_read_b128 v[208:211], v146 offset:7168
	global_load_lds_dwordx4 v[142:143], off
	v_lshl_add_u64 v[142:143], s[52:53], 0, v[138:139]
	s_add_i32 m0, s23, 0xe000
	s_nop 0
	global_load_lds_dwordx4 v[142:143], off
	s_waitcnt vmcnt(8)
	s_waitcnt lgkmcnt(0)
	s_barrier
	v_mfma_f32_16x16x32_bf16 v[126:129], v[148:151], v[180:183], v[126:129]
	s_setprio 1
	v_mfma_f32_16x16x32_bf16 v[122:125], v[156:159], v[180:183], v[122:125]
	v_mfma_f32_16x16x32_bf16 v[110:113], v[148:151], v[188:191], v[110:113]
	v_mfma_f32_16x16x32_bf16 v[106:109], v[156:159], v[188:191], v[106:109]
	v_mfma_f32_16x16x32_bf16 v[94:97], v[148:151], v[196:199], v[94:97]
	v_mfma_f32_16x16x32_bf16 v[90:93], v[156:159], v[196:199], v[90:93]
	v_mfma_f32_16x16x32_bf16 v[78:81], v[148:151], v[204:207], v[78:81]
	v_mfma_f32_16x16x32_bf16 v[74:77], v[156:159], v[204:207], v[74:77]
	v_mfma_f32_16x16x32_bf16 v[126:129], v[152:155], v[184:187], v[126:129]
	v_mfma_f32_16x16x32_bf16 v[122:125], v[160:163], v[184:187], v[122:125]
	v_mfma_f32_16x16x32_bf16 v[110:113], v[152:155], v[192:195], v[110:113]
	v_mfma_f32_16x16x32_bf16 v[106:109], v[160:163], v[192:195], v[106:109]
	v_mfma_f32_16x16x32_bf16 v[94:97], v[152:155], v[200:203], v[94:97]
	v_mfma_f32_16x16x32_bf16 v[90:93], v[160:163], v[200:203], v[90:93]
	v_mfma_f32_16x16x32_bf16 v[78:81], v[152:155], v[208:211], v[78:81]
	v_mfma_f32_16x16x32_bf16 v[74:77], v[160:163], v[208:211], v[74:77]
	s_setprio 0
	s_setprio 1
	v_mfma_f32_16x16x32_bf16 v[118:121], v[164:167], v[180:183], v[118:121]
	v_mfma_f32_16x16x32_bf16 v[114:117], v[172:175], v[180:183], v[114:117]
	v_mfma_f32_16x16x32_bf16 v[102:105], v[164:167], v[188:191], v[102:105]
	v_mfma_f32_16x16x32_bf16 v[98:101], v[172:175], v[188:191], v[98:101]
	v_mfma_f32_16x16x32_bf16 v[86:89], v[164:167], v[196:199], v[86:89]
	v_mfma_f32_16x16x32_bf16 v[82:85], v[172:175], v[196:199], v[82:85]
	v_mfma_f32_16x16x32_bf16 v[70:73], v[164:167], v[204:207], v[70:73]
	v_mfma_f32_16x16x32_bf16 v[66:69], v[172:175], v[204:207], v[66:69]
	v_mfma_f32_16x16x32_bf16 v[118:121], v[168:171], v[184:187], v[118:121]
	v_mfma_f32_16x16x32_bf16 v[114:117], v[176:179], v[184:187], v[114:117]
	v_mfma_f32_16x16x32_bf16 v[102:105], v[168:171], v[192:195], v[102:105]
	v_mfma_f32_16x16x32_bf16 v[98:101], v[176:179], v[192:195], v[98:101]
	v_mfma_f32_16x16x32_bf16 v[86:89], v[168:171], v[200:203], v[86:89]
	v_mfma_f32_16x16x32_bf16 v[82:85], v[176:179], v[200:203], v[82:85]
	v_mfma_f32_16x16x32_bf16 v[70:73], v[168:171], v[208:211], v[70:73]
	v_mfma_f32_16x16x32_bf16 v[66:69], v[176:179], v[208:211], v[66:69]
	s_barrier
	s_setprio 0
	s_add_i32 s91, s91, s14
	v_lshl_add_u64 v[142:143], s[86:87], 0, v[0:1]
	s_mov_b32 m0, s91
	ds_read_b128 v[180:183], v146 offset:16384
	ds_read_b128 v[184:187], v146 offset:17408
	ds_read_b128 v[188:191], v146 offset:18432
	ds_read_b128 v[192:195], v146 offset:19456
	ds_read_b128 v[196:199], v146 offset:20480
	ds_read_b128 v[200:203], v146 offset:21504
	ds_read_b128 v[204:207], v146 offset:22528
	ds_read_b128 v[208:211], v146 offset:23552
	global_load_lds_dwordx4 v[142:143], off
	s_add_i32 m0, s91, 0x2000
	v_lshl_add_u64 v[212:213], s[86:87], 0, v[130:131]
	s_add_u32 s86, s86, s50
	s_addc_u32 s87, s87, 0
	s_add_i32 s83, s83, s14
	global_load_lds_dwordx4 v[212:213], off
	v_lshl_add_u64 v[214:215], s[86:87], 0, v[0:1]
	s_mov_b32 m0, s83
	v_lshl_add_u64 v[216:217], s[86:87], 0, v[130:131]
	global_load_lds_dwordx4 v[214:215], off
	s_add_i32 m0, s83, 0x2000
	v_lshl_add_u64 v[218:219], s[0:1], 0, v[134:135]
	global_load_lds_dwordx4 v[216:217], off
	s_mov_b32 m0, s23
	v_lshl_add_u64 v[220:221], s[0:1], 0, v[132:133]
	global_load_lds_dwordx4 v[218:219], off
	s_mov_b32 m0, s28
	s_nop 0
	global_load_lds_dwordx4 v[220:221], off
	s_waitcnt vmcnt(8)
	s_waitcnt lgkmcnt(0)
	s_barrier
	v_mfma_f32_16x16x32_bf16 v[62:65], v[148:151], v[180:183], v[62:65]
	s_setprio 1
	v_mfma_f32_16x16x32_bf16 v[58:61], v[156:159], v[180:183], v[58:61]
	v_mfma_f32_16x16x32_bf16 v[50:53], v[148:151], v[188:191], v[50:53]
	v_mfma_f32_16x16x32_bf16 v[42:45], v[156:159], v[188:191], v[42:45]
	v_mfma_f32_16x16x32_bf16 v[34:37], v[148:151], v[196:199], v[34:37]
	v_mfma_f32_16x16x32_bf16 v[26:29], v[156:159], v[196:199], v[26:29]
	v_mfma_f32_16x16x32_bf16 v[18:21], v[148:151], v[204:207], v[18:21]
	v_mfma_f32_16x16x32_bf16 v[10:13], v[156:159], v[204:207], v[10:13]
	v_mfma_f32_16x16x32_bf16 v[62:65], v[152:155], v[184:187], v[62:65]
	v_mfma_f32_16x16x32_bf16 v[58:61], v[160:163], v[184:187], v[58:61]
	v_mfma_f32_16x16x32_bf16 v[50:53], v[152:155], v[192:195], v[50:53]
	v_mfma_f32_16x16x32_bf16 v[42:45], v[160:163], v[192:195], v[42:45]
	v_mfma_f32_16x16x32_bf16 v[34:37], v[152:155], v[200:203], v[34:37]
	v_mfma_f32_16x16x32_bf16 v[26:29], v[160:163], v[200:203], v[26:29]
	v_mfma_f32_16x16x32_bf16 v[18:21], v[152:155], v[208:211], v[18:21]
	v_mfma_f32_16x16x32_bf16 v[10:13], v[160:163], v[208:211], v[10:13]
	s_setprio 0
	s_setprio 1
	v_mfma_f32_16x16x32_bf16 v[54:57], v[164:167], v[180:183], v[54:57]
	v_mfma_f32_16x16x32_bf16 v[46:49], v[172:175], v[180:183], v[46:49]
	v_mfma_f32_16x16x32_bf16 v[38:41], v[164:167], v[188:191], v[38:41]
	v_mfma_f32_16x16x32_bf16 v[30:33], v[172:175], v[188:191], v[30:33]
	v_mfma_f32_16x16x32_bf16 v[22:25], v[164:167], v[196:199], v[22:25]
	v_mfma_f32_16x16x32_bf16 v[14:17], v[172:175], v[196:199], v[14:17]
	v_mfma_f32_16x16x32_bf16 v[6:9], v[164:167], v[204:207], v[6:9]
	v_mfma_f32_16x16x32_bf16 v[2:5], v[172:175], v[204:207], v[2:5]
	v_mfma_f32_16x16x32_bf16 v[54:57], v[168:171], v[184:187], v[54:57]
	v_mfma_f32_16x16x32_bf16 v[46:49], v[176:179], v[184:187], v[46:49]
	v_mfma_f32_16x16x32_bf16 v[38:41], v[168:171], v[192:195], v[38:41]
	v_mfma_f32_16x16x32_bf16 v[30:33], v[176:179], v[192:195], v[30:33]
	v_mfma_f32_16x16x32_bf16 v[22:25], v[168:171], v[200:203], v[22:25]
	v_mfma_f32_16x16x32_bf16 v[14:17], v[176:179], v[200:203], v[14:17]
	v_mfma_f32_16x16x32_bf16 v[6:9], v[168:171], v[208:211], v[6:9]
	v_mfma_f32_16x16x32_bf16 v[2:5], v[176:179], v[208:211], v[2:5]
	s_barrier
	s_setprio 0
	s_add_i32 s83, 0, 0x18000
	v_add_u32_e32 v140, s83, v144
	s_add_i32 s86, 0, 0x1c000
	ds_read_b128 v[148:151], v140
	ds_read_b128 v[152:155], v140 offset:1024
	ds_read_b128 v[156:159], v140 offset:2048
	ds_read_b128 v[160:163], v140 offset:3072
	v_add_u32_e32 v140, s86, v144
	ds_read_b128 v[164:167], v140
	ds_read_b128 v[168:171], v140 offset:1024
	ds_read_b128 v[172:175], v140 offset:2048
	ds_read_b128 v[176:179], v140 offset:3072
	s_add_u32 s0, s0, s50
	s_addc_u32 s1, s1, 0
	s_mov_b32 m0, s29
	v_lshl_add_u64 v[222:223], s[0:1], 0, v[134:135]
	ds_read_b128 v[180:183], v146 offset:32768
	ds_read_b128 v[184:187], v146 offset:33792
	ds_read_b128 v[188:191], v146 offset:34816
	ds_read_b128 v[192:195], v146 offset:35840
	ds_read_b128 v[196:199], v146 offset:36864
	ds_read_b128 v[200:203], v146 offset:37888
	ds_read_b128 v[204:207], v146 offset:38912
	ds_read_b128 v[208:211], v146 offset:39936
	global_load_lds_dwordx4 v[222:223], off
	v_lshl_add_u64 v[222:223], s[0:1], 0, v[132:133]
	s_mov_b32 m0, s30
	s_nop 0
	global_load_lds_dwordx4 v[222:223], off
	s_waitcnt vmcnt(8)
	s_waitcnt lgkmcnt(0)
	s_barrier
	v_mfma_f32_16x16x32_bf16 v[126:129], v[148:151], v[180:183], v[126:129]
	s_setprio 1
	v_mfma_f32_16x16x32_bf16 v[122:125], v[156:159], v[180:183], v[122:125]
	v_mfma_f32_16x16x32_bf16 v[110:113], v[148:151], v[188:191], v[110:113]
	v_mfma_f32_16x16x32_bf16 v[106:109], v[156:159], v[188:191], v[106:109]
	v_mfma_f32_16x16x32_bf16 v[94:97], v[148:151], v[196:199], v[94:97]
	v_mfma_f32_16x16x32_bf16 v[90:93], v[156:159], v[196:199], v[90:93]
	v_mfma_f32_16x16x32_bf16 v[78:81], v[148:151], v[204:207], v[78:81]
	v_mfma_f32_16x16x32_bf16 v[74:77], v[156:159], v[204:207], v[74:77]
	v_mfma_f32_16x16x32_bf16 v[126:129], v[152:155], v[184:187], v[126:129]
	v_mfma_f32_16x16x32_bf16 v[122:125], v[160:163], v[184:187], v[122:125]
	v_mfma_f32_16x16x32_bf16 v[110:113], v[152:155], v[192:195], v[110:113]
	v_mfma_f32_16x16x32_bf16 v[106:109], v[160:163], v[192:195], v[106:109]
	v_mfma_f32_16x16x32_bf16 v[94:97], v[152:155], v[200:203], v[94:97]
	v_mfma_f32_16x16x32_bf16 v[90:93], v[160:163], v[200:203], v[90:93]
	v_mfma_f32_16x16x32_bf16 v[78:81], v[152:155], v[208:211], v[78:81]
	v_mfma_f32_16x16x32_bf16 v[74:77], v[160:163], v[208:211], v[74:77]
	s_setprio 0
	s_setprio 1
	v_mfma_f32_16x16x32_bf16 v[118:121], v[164:167], v[180:183], v[118:121]
	v_mfma_f32_16x16x32_bf16 v[114:117], v[172:175], v[180:183], v[114:117]
	v_mfma_f32_16x16x32_bf16 v[102:105], v[164:167], v[188:191], v[102:105]
	v_mfma_f32_16x16x32_bf16 v[98:101], v[172:175], v[188:191], v[98:101]
	v_mfma_f32_16x16x32_bf16 v[86:89], v[164:167], v[196:199], v[86:89]
	v_mfma_f32_16x16x32_bf16 v[82:85], v[172:175], v[196:199], v[82:85]
	v_mfma_f32_16x16x32_bf16 v[70:73], v[164:167], v[204:207], v[70:73]
	v_mfma_f32_16x16x32_bf16 v[66:69], v[172:175], v[204:207], v[66:69]
	v_mfma_f32_16x16x32_bf16 v[118:121], v[168:171], v[184:187], v[118:121]
	v_mfma_f32_16x16x32_bf16 v[114:117], v[176:179], v[184:187], v[114:117]
	v_mfma_f32_16x16x32_bf16 v[102:105], v[168:171], v[192:195], v[102:105]
	v_mfma_f32_16x16x32_bf16 v[98:101], v[176:179], v[192:195], v[98:101]
	v_mfma_f32_16x16x32_bf16 v[86:89], v[168:171], v[200:203], v[86:89]
	v_mfma_f32_16x16x32_bf16 v[82:85], v[176:179], v[200:203], v[82:85]
	v_mfma_f32_16x16x32_bf16 v[70:73], v[168:171], v[208:211], v[70:73]
	v_mfma_f32_16x16x32_bf16 v[66:69], v[176:179], v[208:211], v[66:69]
	s_barrier
	s_setprio 0
	s_add_i32 s0, s83, s14
	v_lshl_add_u64 v[142:143], v[142:143], 0, s[66:67]
	s_mov_b32 m0, s0
	ds_read_b128 v[180:183], v146 offset:49152
	ds_read_b128 v[184:187], v146 offset:50176
	ds_read_b128 v[188:191], v146 offset:51200
	ds_read_b128 v[192:195], v146 offset:52224
	ds_read_b128 v[196:199], v146 offset:53248
	ds_read_b128 v[200:203], v146 offset:54272
	ds_read_b128 v[204:207], v146 offset:55296
	ds_read_b128 v[208:211], v146 offset:56320
	global_load_lds_dwordx4 v[142:143], off
	v_lshl_add_u64 v[142:143], v[212:213], 0, s[66:67]
	s_add_i32 m0, s0, 0x2000
	s_add_i32 s0, s86, s14
	global_load_lds_dwordx4 v[142:143], off
	v_lshl_add_u64 v[142:143], v[214:215], 0, s[66:67]
	s_mov_b32 m0, s0
	s_nop 0
	global_load_lds_dwordx4 v[142:143], off
	v_lshl_add_u64 v[142:143], v[216:217], 0, s[66:67]
	s_add_i32 m0, s0, 0x2000
	s_nop 0
	global_load_lds_dwordx4 v[142:143], off
	v_lshl_add_u64 v[142:143], v[218:219], 0, s[66:67]
	s_mov_b32 m0, s34
	s_nop 0
	global_load_lds_dwordx4 v[142:143], off
	v_lshl_add_u64 v[142:143], v[220:221], 0, s[66:67]
	s_mov_b32 m0, s35
	s_nop 0
	global_load_lds_dwordx4 v[142:143], off
	s_waitcnt vmcnt(8)
	s_waitcnt lgkmcnt(0)
	s_barrier
	v_mfma_f32_16x16x32_bf16 v[62:65], v[148:151], v[180:183], v[62:65]
	s_setprio 1
	v_mfma_f32_16x16x32_bf16 v[58:61], v[156:159], v[180:183], v[58:61]
	v_mfma_f32_16x16x32_bf16 v[50:53], v[148:151], v[188:191], v[50:53]
	v_mfma_f32_16x16x32_bf16 v[42:45], v[156:159], v[188:191], v[42:45]
	v_mfma_f32_16x16x32_bf16 v[34:37], v[148:151], v[196:199], v[34:37]
	v_mfma_f32_16x16x32_bf16 v[26:29], v[156:159], v[196:199], v[26:29]
	v_mfma_f32_16x16x32_bf16 v[18:21], v[148:151], v[204:207], v[18:21]
	v_mfma_f32_16x16x32_bf16 v[10:13], v[156:159], v[204:207], v[10:13]
	v_mfma_f32_16x16x32_bf16 v[62:65], v[152:155], v[184:187], v[62:65]
	v_mfma_f32_16x16x32_bf16 v[58:61], v[160:163], v[184:187], v[58:61]
	v_mfma_f32_16x16x32_bf16 v[50:53], v[152:155], v[192:195], v[50:53]
	v_mfma_f32_16x16x32_bf16 v[42:45], v[160:163], v[192:195], v[42:45]
	v_mfma_f32_16x16x32_bf16 v[34:37], v[152:155], v[200:203], v[34:37]
	v_mfma_f32_16x16x32_bf16 v[26:29], v[160:163], v[200:203], v[26:29]
	v_mfma_f32_16x16x32_bf16 v[18:21], v[152:155], v[208:211], v[18:21]
	v_mfma_f32_16x16x32_bf16 v[10:13], v[160:163], v[208:211], v[10:13]
	s_setprio 0
	s_setprio 1
	v_mfma_f32_16x16x32_bf16 v[54:57], v[164:167], v[180:183], v[54:57]
	v_mfma_f32_16x16x32_bf16 v[46:49], v[172:175], v[180:183], v[46:49]
	v_mfma_f32_16x16x32_bf16 v[38:41], v[164:167], v[188:191], v[38:41]
	v_mfma_f32_16x16x32_bf16 v[30:33], v[172:175], v[188:191], v[30:33]
	v_mfma_f32_16x16x32_bf16 v[22:25], v[164:167], v[196:199], v[22:25]
	v_mfma_f32_16x16x32_bf16 v[14:17], v[172:175], v[196:199], v[14:17]
	v_mfma_f32_16x16x32_bf16 v[6:9], v[164:167], v[204:207], v[6:9]
	v_mfma_f32_16x16x32_bf16 v[2:5], v[172:175], v[204:207], v[2:5]
	v_mfma_f32_16x16x32_bf16 v[54:57], v[168:171], v[184:187], v[54:57]
	v_mfma_f32_16x16x32_bf16 v[46:49], v[176:179], v[184:187], v[46:49]
	v_mfma_f32_16x16x32_bf16 v[38:41], v[168:171], v[192:195], v[38:41]
	v_mfma_f32_16x16x32_bf16 v[30:33], v[176:179], v[192:195], v[30:33]
	v_mfma_f32_16x16x32_bf16 v[22:25], v[168:171], v[200:203], v[22:25]
	v_mfma_f32_16x16x32_bf16 v[14:17], v[176:179], v[200:203], v[14:17]
	v_mfma_f32_16x16x32_bf16 v[6:9], v[168:171], v[208:211], v[6:9]
	v_mfma_f32_16x16x32_bf16 v[2:5], v[176:179], v[208:211], v[2:5]
	s_barrier
	s_setprio 0
	s_add_u32 s52, s52, 0x100
	s_addc_u32 s53, s53, 0
	s_add_u32 s75, s75, 0x100
	s_addc_u32 s78, s78, 0
	s_cmp_ge_u32 s79, s31
	s_mov_b32 s0, s79
	s_cbranch_scc0 .LBB0_414
	s_and_b64 vcc, exec, s[12:13]
	s_cbranch_vccz .LBB0_417
	s_barrier

.LBB0_455:
	s_add_i32 s25, s0, 2
	s_add_u32 s41, s2, 0x80
	s_addc_u32 s1, s3, 0
	s_add_i32 s53, 0, 0x10000
	s_cmp_eq_u32 s64, s0
	s_cselect_b32 s1, s37, s1
	s_cselect_b32 s0, s36, s41
	s_cselect_b32 s87, s39, s7
	s_cselect_b32 s86, s38, s6
	s_add_i32 s41, 0, 0x14000
	v_add_u32_e32 v142, s53, v251
	v_add_u32_e32 v158, s41, v251
	ds_read_b128 v[122:125], v142
	ds_read_b128 v[126:129], v142 offset:1024
	ds_read_b128 v[138:141], v142 offset:2048
	ds_read_b128 v[142:145], v142 offset:3072
	ds_read_b128 v[146:149], v158
	ds_read_b128 v[150:153], v158 offset:1024
	ds_read_b128 v[154:157], v158 offset:2048
	ds_read_b128 v[158:161], v158 offset:3072
	v_lshl_add_u64 v[204:205], s[2:3], 0, v[200:201]
	s_add_i32 m0, s15, 0xc000
	ds_read_b128 v[162:165], v252
	ds_read_b128 v[166:169], v252 offset:1024
	ds_read_b128 v[170:173], v252 offset:2048
	ds_read_b128 v[174:177], v252 offset:3072
	ds_read_b128 v[178:181], v252 offset:4096
	ds_read_b128 v[182:185], v252 offset:5120
	ds_read_b128 v[186:189], v252 offset:6144
	ds_read_b128 v[190:193], v252 offset:7168
	global_load_lds_dwordx4 v[204:205], off
	v_lshl_add_u64 v[204:205], s[2:3], 0, v[202:203]
	s_add_i32 m0, s15, 0xe000
	s_nop 0
	global_load_lds_dwordx4 v[204:205], off
	s_waitcnt vmcnt(8)
	s_waitcnt lgkmcnt(0)
	s_barrier
	v_mfma_f32_16x16x32_bf16 v[134:137], v[122:125], v[162:165], v[134:137]
	s_setprio 1
	v_mfma_f32_16x16x32_bf16 v[130:133], v[138:141], v[162:165], v[130:133]
	v_mfma_f32_16x16x32_bf16 v[110:113], v[122:125], v[170:173], v[110:113]
	v_mfma_f32_16x16x32_bf16 v[106:109], v[138:141], v[170:173], v[106:109]
	v_mfma_f32_16x16x32_bf16 v[94:97], v[122:125], v[178:181], v[94:97]
	v_mfma_f32_16x16x32_bf16 v[90:93], v[138:141], v[178:181], v[90:93]
	v_mfma_f32_16x16x32_bf16 v[78:81], v[122:125], v[186:189], v[78:81]
	v_mfma_f32_16x16x32_bf16 v[74:77], v[138:141], v[186:189], v[74:77]
	v_mfma_f32_16x16x32_bf16 v[134:137], v[126:129], v[166:169], v[134:137]
	v_mfma_f32_16x16x32_bf16 v[130:133], v[142:145], v[166:169], v[130:133]
	v_mfma_f32_16x16x32_bf16 v[110:113], v[126:129], v[174:177], v[110:113]
	v_mfma_f32_16x16x32_bf16 v[106:109], v[142:145], v[174:177], v[106:109]
	v_mfma_f32_16x16x32_bf16 v[94:97], v[126:129], v[182:185], v[94:97]
	v_mfma_f32_16x16x32_bf16 v[90:93], v[142:145], v[182:185], v[90:93]
	v_mfma_f32_16x16x32_bf16 v[78:81], v[126:129], v[190:193], v[78:81]
	v_mfma_f32_16x16x32_bf16 v[74:77], v[142:145], v[190:193], v[74:77]
	s_setprio 0
	s_setprio 1
	v_mfma_f32_16x16x32_bf16 v[118:121], v[146:149], v[162:165], v[118:121]
	v_mfma_f32_16x16x32_bf16 v[114:117], v[154:157], v[162:165], v[114:117]
	v_mfma_f32_16x16x32_bf16 v[102:105], v[146:149], v[170:173], v[102:105]
	v_mfma_f32_16x16x32_bf16 v[98:101], v[154:157], v[170:173], v[98:101]
	v_mfma_f32_16x16x32_bf16 v[86:89], v[146:149], v[178:181], v[86:89]
	v_mfma_f32_16x16x32_bf16 v[82:85], v[154:157], v[178:181], v[82:85]
	v_mfma_f32_16x16x32_bf16 v[70:73], v[146:149], v[186:189], v[70:73]
	v_mfma_f32_16x16x32_bf16 v[66:69], v[154:157], v[186:189], v[66:69]
	v_mfma_f32_16x16x32_bf16 v[118:121], v[150:153], v[166:169], v[118:121]
	v_mfma_f32_16x16x32_bf16 v[114:117], v[158:161], v[166:169], v[114:117]
	v_mfma_f32_16x16x32_bf16 v[102:105], v[150:153], v[174:177], v[102:105]
	v_mfma_f32_16x16x32_bf16 v[98:101], v[158:161], v[174:177], v[98:101]
	v_mfma_f32_16x16x32_bf16 v[86:89], v[150:153], v[182:185], v[86:89]
	v_mfma_f32_16x16x32_bf16 v[82:85], v[158:161], v[182:185], v[82:85]
	v_mfma_f32_16x16x32_bf16 v[70:73], v[150:153], v[190:193], v[70:73]
	v_mfma_f32_16x16x32_bf16 v[66:69], v[158:161], v[190:193], v[66:69]
	s_barrier
	s_setprio 0
	s_add_i32 s53, s53, s14
	v_lshl_add_u64 v[204:205], s[86:87], 0, v[0:1]
	s_mov_b32 m0, s53
	ds_read_b128 v[162:165], v252 offset:16384
	ds_read_b128 v[166:169], v252 offset:17408
	ds_read_b128 v[170:173], v252 offset:18432
	ds_read_b128 v[174:177], v252 offset:19456
	ds_read_b128 v[178:181], v252 offset:20480
	ds_read_b128 v[182:185], v252 offset:21504
	ds_read_b128 v[186:189], v252 offset:22528
	ds_read_b128 v[190:193], v252 offset:23552
	global_load_lds_dwordx4 v[204:205], off
	s_add_i32 m0, s53, 0x2000
	v_lshl_add_u64 v[206:207], s[86:87], 0, v[198:199]
	s_add_u32 s86, s86, s50
	s_addc_u32 s87, s87, 0
	s_add_i32 s41, s41, s14
	global_load_lds_dwordx4 v[206:207], off
	v_lshl_add_u64 v[208:209], s[86:87], 0, v[0:1]
	s_mov_b32 m0, s41
	v_lshl_add_u64 v[210:211], s[86:87], 0, v[198:199]
	global_load_lds_dwordx4 v[208:209], off
	s_add_i32 m0, s41, 0x2000
	v_lshl_add_u64 v[212:213], s[0:1], 0, v[194:195]
	global_load_lds_dwordx4 v[210:211], off
	s_mov_b32 m0, s15
	v_lshl_add_u64 v[214:215], s[0:1], 0, v[196:197]
	global_load_lds_dwordx4 v[212:213], off
	s_mov_b32 m0, s18
	s_nop 0
	global_load_lds_dwordx4 v[214:215], off
	s_waitcnt vmcnt(8)
	s_waitcnt lgkmcnt(0)
	s_barrier
	v_mfma_f32_16x16x32_bf16 v[62:65], v[122:125], v[162:165], v[62:65]
	s_setprio 1
	v_mfma_f32_16x16x32_bf16 v[58:61], v[138:141], v[162:165], v[58:61]
	v_mfma_f32_16x16x32_bf16 v[46:49], v[122:125], v[170:173], v[46:49]
	v_mfma_f32_16x16x32_bf16 v[42:45], v[138:141], v[170:173], v[42:45]
	v_mfma_f32_16x16x32_bf16 v[30:33], v[122:125], v[178:181], v[30:33]
	v_mfma_f32_16x16x32_bf16 v[26:29], v[138:141], v[178:181], v[26:29]
	v_mfma_f32_16x16x32_bf16 v[14:17], v[122:125], v[186:189], v[14:17]
	v_mfma_f32_16x16x32_bf16 v[10:13], v[138:141], v[186:189], v[10:13]
	v_mfma_f32_16x16x32_bf16 v[62:65], v[126:129], v[166:169], v[62:65]
	v_mfma_f32_16x16x32_bf16 v[58:61], v[142:145], v[166:169], v[58:61]
	v_mfma_f32_16x16x32_bf16 v[46:49], v[126:129], v[174:177], v[46:49]
	v_mfma_f32_16x16x32_bf16 v[42:45], v[142:145], v[174:177], v[42:45]
	v_mfma_f32_16x16x32_bf16 v[30:33], v[126:129], v[182:185], v[30:33]
	v_mfma_f32_16x16x32_bf16 v[26:29], v[142:145], v[182:185], v[26:29]
	v_mfma_f32_16x16x32_bf16 v[14:17], v[126:129], v[190:193], v[14:17]
	v_mfma_f32_16x16x32_bf16 v[10:13], v[142:145], v[190:193], v[10:13]
	s_setprio 0
	s_setprio 1
	v_mfma_f32_16x16x32_bf16 v[54:57], v[146:149], v[162:165], v[54:57]
	v_mfma_f32_16x16x32_bf16 v[50:53], v[154:157], v[162:165], v[50:53]
	v_mfma_f32_16x16x32_bf16 v[38:41], v[146:149], v[170:173], v[38:41]
	v_mfma_f32_16x16x32_bf16 v[34:37], v[154:157], v[170:173], v[34:37]
	v_mfma_f32_16x16x32_bf16 v[22:25], v[146:149], v[178:181], v[22:25]
	v_mfma_f32_16x16x32_bf16 v[18:21], v[154:157], v[178:181], v[18:21]
	v_mfma_f32_16x16x32_bf16 v[6:9], v[146:149], v[186:189], v[6:9]
	v_mfma_f32_16x16x32_bf16 v[2:5], v[154:157], v[186:189], v[2:5]
	v_mfma_f32_16x16x32_bf16 v[54:57], v[150:153], v[166:169], v[54:57]
	v_mfma_f32_16x16x32_bf16 v[50:53], v[158:161], v[166:169], v[50:53]
	v_mfma_f32_16x16x32_bf16 v[38:41], v[150:153], v[174:177], v[38:41]
	v_mfma_f32_16x16x32_bf16 v[34:37], v[158:161], v[174:177], v[34:37]
	v_mfma_f32_16x16x32_bf16 v[22:25], v[150:153], v[182:185], v[22:25]
	v_mfma_f32_16x16x32_bf16 v[18:21], v[158:161], v[182:185], v[18:21]
	v_mfma_f32_16x16x32_bf16 v[6:9], v[150:153], v[190:193], v[6:9]
	v_mfma_f32_16x16x32_bf16 v[2:5], v[158:161], v[190:193], v[2:5]
	s_barrier
	s_setprio 0
	s_add_i32 s41, 0, 0x18000
	s_add_i32 s53, 0, 0x1c000
	v_add_u32_e32 v142, s41, v251
	v_add_u32_e32 v158, s53, v251
	ds_read_b128 v[122:125], v142
	ds_read_b128 v[126:129], v142 offset:1024
	ds_read_b128 v[138:141], v142 offset:2048
	ds_read_b128 v[142:145], v142 offset:3072
	ds_read_b128 v[146:149], v158
	ds_read_b128 v[150:153], v158 offset:1024
	ds_read_b128 v[154:157], v158 offset:2048
	ds_read_b128 v[158:161], v158 offset:3072
	s_add_u32 s0, s0, s50
	s_addc_u32 s1, s1, 0
	s_mov_b32 m0, s19
	v_lshl_add_u64 v[216:217], s[0:1], 0, v[194:195]
	ds_read_b128 v[162:165], v252 offset:32768
	ds_read_b128 v[166:169], v252 offset:33792
	ds_read_b128 v[170:173], v252 offset:34816
	ds_read_b128 v[174:177], v252 offset:35840
	ds_read_b128 v[178:181], v252 offset:36864
	ds_read_b128 v[182:185], v252 offset:37888
	ds_read_b128 v[186:189], v252 offset:38912
	ds_read_b128 v[190:193], v252 offset:39936
	global_load_lds_dwordx4 v[216:217], off
	v_lshl_add_u64 v[216:217], s[0:1], 0, v[196:197]
	s_mov_b32 m0, s22
	s_nop 0
	global_load_lds_dwordx4 v[216:217], off
	s_waitcnt vmcnt(8)
	s_waitcnt lgkmcnt(0)
	s_barrier
	v_mfma_f32_16x16x32_bf16 v[134:137], v[122:125], v[162:165], v[134:137]
	s_setprio 1
	v_mfma_f32_16x16x32_bf16 v[130:133], v[138:141], v[162:165], v[130:133]
	v_mfma_f32_16x16x32_bf16 v[110:113], v[122:125], v[170:173], v[110:113]
	v_mfma_f32_16x16x32_bf16 v[106:109], v[138:141], v[170:173], v[106:109]
	v_mfma_f32_16x16x32_bf16 v[94:97], v[122:125], v[178:181], v[94:97]
	v_mfma_f32_16x16x32_bf16 v[90:93], v[138:141], v[178:181], v[90:93]
	v_mfma_f32_16x16x32_bf16 v[78:81], v[122:125], v[186:189], v[78:81]
	v_mfma_f32_16x16x32_bf16 v[74:77], v[138:141], v[186:189], v[74:77]
	v_mfma_f32_16x16x32_bf16 v[134:137], v[126:129], v[166:169], v[134:137]
	v_mfma_f32_16x16x32_bf16 v[130:133], v[142:145], v[166:169], v[130:133]
	v_mfma_f32_16x16x32_bf16 v[110:113], v[126:129], v[174:177], v[110:113]
	v_mfma_f32_16x16x32_bf16 v[106:109], v[142:145], v[174:177], v[106:109]
	v_mfma_f32_16x16x32_bf16 v[94:97], v[126:129], v[182:185], v[94:97]
	v_mfma_f32_16x16x32_bf16 v[90:93], v[142:145], v[182:185], v[90:93]
	v_mfma_f32_16x16x32_bf16 v[78:81], v[126:129], v[190:193], v[78:81]
	v_mfma_f32_16x16x32_bf16 v[74:77], v[142:145], v[190:193], v[74:77]
	s_setprio 0
	s_setprio 1
	v_mfma_f32_16x16x32_bf16 v[118:121], v[146:149], v[162:165], v[118:121]
	v_mfma_f32_16x16x32_bf16 v[114:117], v[154:157], v[162:165], v[114:117]
	v_mfma_f32_16x16x32_bf16 v[102:105], v[146:149], v[170:173], v[102:105]
	v_mfma_f32_16x16x32_bf16 v[98:101], v[154:157], v[170:173], v[98:101]
	v_mfma_f32_16x16x32_bf16 v[86:89], v[146:149], v[178:181], v[86:89]
	v_mfma_f32_16x16x32_bf16 v[82:85], v[154:157], v[178:181], v[82:85]
	v_mfma_f32_16x16x32_bf16 v[70:73], v[146:149], v[186:189], v[70:73]
	v_mfma_f32_16x16x32_bf16 v[66:69], v[154:157], v[186:189], v[66:69]
	v_mfma_f32_16x16x32_bf16 v[118:121], v[150:153], v[166:169], v[118:121]
	v_mfma_f32_16x16x32_bf16 v[114:117], v[158:161], v[166:169], v[114:117]
	v_mfma_f32_16x16x32_bf16 v[102:105], v[150:153], v[174:177], v[102:105]
	v_mfma_f32_16x16x32_bf16 v[98:101], v[158:161], v[174:177], v[98:101]
	v_mfma_f32_16x16x32_bf16 v[86:89], v[150:153], v[182:185], v[86:89]
	v_mfma_f32_16x16x32_bf16 v[82:85], v[158:161], v[182:185], v[82:85]
	v_mfma_f32_16x16x32_bf16 v[70:73], v[150:153], v[190:193], v[70:73]
	v_mfma_f32_16x16x32_bf16 v[66:69], v[158:161], v[190:193], v[66:69]
	s_barrier
	s_setprio 0
	s_add_i32 s0, s41, s14
	v_lshl_add_u64 v[204:205], v[204:205], 0, s[66:67]
	s_mov_b32 m0, s0
	ds_read_b128 v[162:165], v252 offset:49152
	ds_read_b128 v[166:169], v252 offset:50176
	ds_read_b128 v[170:173], v252 offset:51200
	ds_read_b128 v[174:177], v252 offset:52224
	ds_read_b128 v[178:181], v252 offset:53248
	ds_read_b128 v[182:185], v252 offset:54272
	ds_read_b128 v[186:189], v252 offset:55296
	ds_read_b128 v[190:193], v252 offset:56320
	global_load_lds_dwordx4 v[204:205], off
	v_lshl_add_u64 v[204:205], v[206:207], 0, s[66:67]
	s_add_i32 m0, s0, 0x2000
	s_add_i32 s0, s53, s14
	global_load_lds_dwordx4 v[204:205], off
	v_lshl_add_u64 v[204:205], v[208:209], 0, s[66:67]
	s_mov_b32 m0, s0
	s_nop 0
	global_load_lds_dwordx4 v[204:205], off
	v_lshl_add_u64 v[204:205], v[210:211], 0, s[66:67]
	s_add_i32 m0, s0, 0x2000
	s_nop 0
	global_load_lds_dwordx4 v[204:205], off
	v_lshl_add_u64 v[204:205], v[212:213], 0, s[66:67]
	s_mov_b32 m0, s43
	s_nop 0
	global_load_lds_dwordx4 v[204:205], off
	v_lshl_add_u64 v[204:205], v[214:215], 0, s[66:67]
	s_mov_b32 m0, s55
	s_nop 0
	global_load_lds_dwordx4 v[204:205], off
	s_waitcnt vmcnt(8)
	s_waitcnt lgkmcnt(0)
	s_barrier
	v_mfma_f32_16x16x32_bf16 v[62:65], v[122:125], v[162:165], v[62:65]
	s_setprio 1
	v_mfma_f32_16x16x32_bf16 v[58:61], v[138:141], v[162:165], v[58:61]
	v_mfma_f32_16x16x32_bf16 v[46:49], v[122:125], v[170:173], v[46:49]
	v_mfma_f32_16x16x32_bf16 v[42:45], v[138:141], v[170:173], v[42:45]
	v_mfma_f32_16x16x32_bf16 v[30:33], v[122:125], v[178:181], v[30:33]
	v_mfma_f32_16x16x32_bf16 v[26:29], v[138:141], v[178:181], v[26:29]
	v_mfma_f32_16x16x32_bf16 v[14:17], v[122:125], v[186:189], v[14:17]
	v_mfma_f32_16x16x32_bf16 v[10:13], v[138:141], v[186:189], v[10:13]
	v_mfma_f32_16x16x32_bf16 v[62:65], v[126:129], v[166:169], v[62:65]
	v_mfma_f32_16x16x32_bf16 v[58:61], v[142:145], v[166:169], v[58:61]
	v_mfma_f32_16x16x32_bf16 v[46:49], v[126:129], v[174:177], v[46:49]
	v_mfma_f32_16x16x32_bf16 v[42:45], v[142:145], v[174:177], v[42:45]
	v_mfma_f32_16x16x32_bf16 v[30:33], v[126:129], v[182:185], v[30:33]
	v_mfma_f32_16x16x32_bf16 v[26:29], v[142:145], v[182:185], v[26:29]
	v_mfma_f32_16x16x32_bf16 v[14:17], v[126:129], v[190:193], v[14:17]
	v_mfma_f32_16x16x32_bf16 v[10:13], v[142:145], v[190:193], v[10:13]
	s_setprio 0
	s_setprio 1
	v_mfma_f32_16x16x32_bf16 v[54:57], v[146:149], v[162:165], v[54:57]
	v_mfma_f32_16x16x32_bf16 v[50:53], v[154:157], v[162:165], v[50:53]
	v_mfma_f32_16x16x32_bf16 v[38:41], v[146:149], v[170:173], v[38:41]
	v_mfma_f32_16x16x32_bf16 v[34:37], v[154:157], v[170:173], v[34:37]
	v_mfma_f32_16x16x32_bf16 v[22:25], v[146:149], v[178:181], v[22:25]
	v_mfma_f32_16x16x32_bf16 v[18:21], v[154:157], v[178:181], v[18:21]
	v_mfma_f32_16x16x32_bf16 v[6:9], v[146:149], v[186:189], v[6:9]
	v_mfma_f32_16x16x32_bf16 v[2:5], v[154:157], v[186:189], v[2:5]
	v_mfma_f32_16x16x32_bf16 v[54:57], v[150:153], v[166:169], v[54:57]
	v_mfma_f32_16x16x32_bf16 v[50:53], v[158:161], v[166:169], v[50:53]
	v_mfma_f32_16x16x32_bf16 v[38:41], v[150:153], v[174:177], v[38:41]
	v_mfma_f32_16x16x32_bf16 v[34:37], v[158:161], v[174:177], v[34:37]
	v_mfma_f32_16x16x32_bf16 v[22:25], v[150:153], v[182:185], v[22:25]
	v_mfma_f32_16x16x32_bf16 v[18:21], v[158:161], v[182:185], v[18:21]
	v_mfma_f32_16x16x32_bf16 v[6:9], v[150:153], v[190:193], v[6:9]
	v_mfma_f32_16x16x32_bf16 v[2:5], v[158:161], v[190:193], v[2:5]
	s_barrier
	s_setprio 0
	s_add_u32 s2, s2, 0x100
	s_addc_u32 s3, s3, 0
	s_add_u32 s6, s6, 0x100
	s_addc_u32 s7, s7, 0
	s_cmp_ge_u32 s25, s23
	s_mov_b32 s0, s25
	s_cbranch_scc0 .LBB0_455
	s_and_b64 vcc, exec, s[34:35]
	s_cbranch_vccz .LBB0_458
	s_barrier

.LBB0_519:
	s_add_i32 s25, s0, 2
	s_add_u32 s39, s2, 0x80
	s_addc_u32 s1, s3, 0
	s_add_i32 s86, 0, 0x10000
	s_cmp_eq_u32 s68, s0
	s_cselect_b32 s1, s35, s1
	s_cselect_b32 s0, s34, s39
	s_cselect_b32 s53, s37, s7
	s_cselect_b32 s52, s36, s6
	s_add_i32 s39, 0, 0x14000
	v_add_u32_e32 v134, s86, v240
	v_add_u32_e32 v158, s39, v240
	ds_read_b128 v[114:117], v134
	ds_read_b128 v[122:125], v134 offset:1024
	ds_read_b128 v[126:129], v134 offset:2048
	ds_read_b128 v[134:137], v134 offset:3072
	ds_read_b128 v[146:149], v158
	ds_read_b128 v[150:153], v158 offset:1024
	ds_read_b128 v[154:157], v158 offset:2048
	ds_read_b128 v[158:161], v158 offset:3072
	v_lshl_add_u64 v[204:205], s[2:3], 0, v[196:197]
	s_add_i32 m0, s19, 0xc000
	ds_read_b128 v[162:165], v241
	ds_read_b128 v[166:169], v241 offset:1024
	ds_read_b128 v[170:173], v241 offset:2048
	ds_read_b128 v[174:177], v241 offset:3072
	ds_read_b128 v[178:181], v241 offset:4096
	ds_read_b128 v[182:185], v241 offset:5120
	ds_read_b128 v[186:189], v241 offset:6144
	ds_read_b128 v[200:203], v241 offset:7168
	global_load_lds_dwordx4 v[204:205], off
	v_lshl_add_u64 v[204:205], s[2:3], 0, v[198:199]
	s_add_i32 m0, s19, 0xe000
	s_nop 0
	global_load_lds_dwordx4 v[204:205], off
	s_waitcnt vmcnt(8)
	s_waitcnt lgkmcnt(0)
	s_barrier
	v_mfma_f32_16x16x32_bf16 v[142:145], v[114:117], v[162:165], v[142:145]
	s_setprio 1
	v_mfma_f32_16x16x32_bf16 v[138:141], v[126:129], v[162:165], v[138:141]
	v_mfma_f32_16x16x32_bf16 v[110:113], v[114:117], v[170:173], v[110:113]
	v_mfma_f32_16x16x32_bf16 v[106:109], v[126:129], v[170:173], v[106:109]
	v_mfma_f32_16x16x32_bf16 v[94:97], v[114:117], v[178:181], v[94:97]
	v_mfma_f32_16x16x32_bf16 v[90:93], v[126:129], v[178:181], v[90:93]
	v_mfma_f32_16x16x32_bf16 v[78:81], v[114:117], v[186:189], v[78:81]
	v_mfma_f32_16x16x32_bf16 v[74:77], v[126:129], v[186:189], v[74:77]
	v_mfma_f32_16x16x32_bf16 v[142:145], v[122:125], v[166:169], v[142:145]
	v_mfma_f32_16x16x32_bf16 v[138:141], v[134:137], v[166:169], v[138:141]
	v_mfma_f32_16x16x32_bf16 v[110:113], v[122:125], v[174:177], v[110:113]
	v_mfma_f32_16x16x32_bf16 v[106:109], v[134:137], v[174:177], v[106:109]
	v_mfma_f32_16x16x32_bf16 v[94:97], v[122:125], v[182:185], v[94:97]
	v_mfma_f32_16x16x32_bf16 v[90:93], v[134:137], v[182:185], v[90:93]
	v_mfma_f32_16x16x32_bf16 v[78:81], v[122:125], v[200:203], v[78:81]
	v_mfma_f32_16x16x32_bf16 v[74:77], v[134:137], v[200:203], v[74:77]
	s_setprio 0
	s_setprio 1
	v_mfma_f32_16x16x32_bf16 v[130:133], v[146:149], v[162:165], v[130:133]
	v_mfma_f32_16x16x32_bf16 v[118:121], v[154:157], v[162:165], v[118:121]
	v_mfma_f32_16x16x32_bf16 v[102:105], v[146:149], v[170:173], v[102:105]
	v_mfma_f32_16x16x32_bf16 v[98:101], v[154:157], v[170:173], v[98:101]
	v_mfma_f32_16x16x32_bf16 v[86:89], v[146:149], v[178:181], v[86:89]
	v_mfma_f32_16x16x32_bf16 v[82:85], v[154:157], v[178:181], v[82:85]
	v_mfma_f32_16x16x32_bf16 v[70:73], v[146:149], v[186:189], v[70:73]
	v_mfma_f32_16x16x32_bf16 v[66:69], v[154:157], v[186:189], v[66:69]
	v_mfma_f32_16x16x32_bf16 v[130:133], v[150:153], v[166:169], v[130:133]
	v_mfma_f32_16x16x32_bf16 v[118:121], v[158:161], v[166:169], v[118:121]
	v_mfma_f32_16x16x32_bf16 v[102:105], v[150:153], v[174:177], v[102:105]
	v_mfma_f32_16x16x32_bf16 v[98:101], v[158:161], v[174:177], v[98:101]
	v_mfma_f32_16x16x32_bf16 v[86:89], v[150:153], v[182:185], v[86:89]
	v_mfma_f32_16x16x32_bf16 v[82:85], v[158:161], v[182:185], v[82:85]
	v_mfma_f32_16x16x32_bf16 v[70:73], v[150:153], v[200:203], v[70:73]
	v_mfma_f32_16x16x32_bf16 v[66:69], v[158:161], v[200:203], v[66:69]
	s_barrier
	s_setprio 0
	s_add_i32 s86, s86, s18
	v_lshl_add_u64 v[204:205], s[52:53], 0, v[0:1]
	s_mov_b32 m0, s86
	ds_read_b128 v[162:165], v241 offset:16384
	ds_read_b128 v[166:169], v241 offset:17408
	ds_read_b128 v[170:173], v241 offset:18432
	ds_read_b128 v[174:177], v241 offset:19456
	ds_read_b128 v[178:181], v241 offset:20480
	ds_read_b128 v[182:185], v241 offset:21504
	ds_read_b128 v[186:189], v241 offset:22528
	ds_read_b128 v[200:203], v241 offset:23552
	global_load_lds_dwordx4 v[204:205], off
	s_add_i32 m0, s86, 0x2000
	v_lshl_add_u64 v[206:207], s[52:53], 0, v[194:195]
	s_add_u32 s52, s52, s50
	s_addc_u32 s53, s53, 0
	s_add_i32 s39, s39, s18
	global_load_lds_dwordx4 v[206:207], off
	v_lshl_add_u64 v[208:209], s[52:53], 0, v[0:1]
	s_mov_b32 m0, s39
	v_lshl_add_u64 v[210:211], s[52:53], 0, v[194:195]
	global_load_lds_dwordx4 v[208:209], off
	s_add_i32 m0, s39, 0x2000
	v_lshl_add_u64 v[212:213], s[0:1], 0, v[190:191]
	global_load_lds_dwordx4 v[210:211], off
	s_mov_b32 m0, s19
	v_lshl_add_u64 v[214:215], s[0:1], 0, v[192:193]
	global_load_lds_dwordx4 v[212:213], off
	s_mov_b32 m0, s22
	s_nop 0
	global_load_lds_dwordx4 v[214:215], off
	s_waitcnt vmcnt(8)
	s_waitcnt lgkmcnt(0)
	s_barrier
	v_mfma_f32_16x16x32_bf16 v[62:65], v[114:117], v[162:165], v[62:65]
	s_setprio 1
	v_mfma_f32_16x16x32_bf16 v[58:61], v[126:129], v[162:165], v[58:61]
	v_mfma_f32_16x16x32_bf16 v[46:49], v[114:117], v[170:173], v[46:49]
	v_mfma_f32_16x16x32_bf16 v[42:45], v[126:129], v[170:173], v[42:45]
	v_mfma_f32_16x16x32_bf16 v[30:33], v[114:117], v[178:181], v[30:33]
	v_mfma_f32_16x16x32_bf16 v[26:29], v[126:129], v[178:181], v[26:29]
	v_mfma_f32_16x16x32_bf16 v[14:17], v[114:117], v[186:189], v[14:17]
	v_mfma_f32_16x16x32_bf16 v[10:13], v[126:129], v[186:189], v[10:13]
	v_mfma_f32_16x16x32_bf16 v[62:65], v[122:125], v[166:169], v[62:65]
	v_mfma_f32_16x16x32_bf16 v[58:61], v[134:137], v[166:169], v[58:61]
	v_mfma_f32_16x16x32_bf16 v[46:49], v[122:125], v[174:177], v[46:49]
	v_mfma_f32_16x16x32_bf16 v[42:45], v[134:137], v[174:177], v[42:45]
	v_mfma_f32_16x16x32_bf16 v[30:33], v[122:125], v[182:185], v[30:33]
	v_mfma_f32_16x16x32_bf16 v[26:29], v[134:137], v[182:185], v[26:29]
	v_mfma_f32_16x16x32_bf16 v[14:17], v[122:125], v[200:203], v[14:17]
	v_mfma_f32_16x16x32_bf16 v[10:13], v[134:137], v[200:203], v[10:13]
	s_setprio 0
	s_setprio 1
	v_mfma_f32_16x16x32_bf16 v[54:57], v[146:149], v[162:165], v[54:57]
	v_mfma_f32_16x16x32_bf16 v[50:53], v[154:157], v[162:165], v[50:53]
	v_mfma_f32_16x16x32_bf16 v[38:41], v[146:149], v[170:173], v[38:41]
	v_mfma_f32_16x16x32_bf16 v[34:37], v[154:157], v[170:173], v[34:37]
	v_mfma_f32_16x16x32_bf16 v[22:25], v[146:149], v[178:181], v[22:25]
	v_mfma_f32_16x16x32_bf16 v[18:21], v[154:157], v[178:181], v[18:21]
	v_mfma_f32_16x16x32_bf16 v[6:9], v[146:149], v[186:189], v[6:9]
	v_mfma_f32_16x16x32_bf16 v[2:5], v[154:157], v[186:189], v[2:5]
	v_mfma_f32_16x16x32_bf16 v[54:57], v[150:153], v[166:169], v[54:57]
	v_mfma_f32_16x16x32_bf16 v[50:53], v[158:161], v[166:169], v[50:53]
	v_mfma_f32_16x16x32_bf16 v[38:41], v[150:153], v[174:177], v[38:41]
	v_mfma_f32_16x16x32_bf16 v[34:37], v[158:161], v[174:177], v[34:37]
	v_mfma_f32_16x16x32_bf16 v[22:25], v[150:153], v[182:185], v[22:25]
	v_mfma_f32_16x16x32_bf16 v[18:21], v[158:161], v[182:185], v[18:21]
	v_mfma_f32_16x16x32_bf16 v[6:9], v[150:153], v[200:203], v[6:9]
	v_mfma_f32_16x16x32_bf16 v[2:5], v[158:161], v[200:203], v[2:5]
	s_barrier
	s_setprio 0
	s_add_i32 s39, 0, 0x18000
	s_add_i32 s52, 0, 0x1c000
	v_add_u32_e32 v134, s39, v240
	v_add_u32_e32 v158, s52, v240
	ds_read_b128 v[114:117], v134
	ds_read_b128 v[122:125], v134 offset:1024
	ds_read_b128 v[126:129], v134 offset:2048
	ds_read_b128 v[134:137], v134 offset:3072
	ds_read_b128 v[146:149], v158
	ds_read_b128 v[150:153], v158 offset:1024
	ds_read_b128 v[154:157], v158 offset:2048
	ds_read_b128 v[158:161], v158 offset:3072
	s_add_u32 s0, s0, s50
	s_addc_u32 s1, s1, 0
	s_mov_b32 m0, s23
	v_lshl_add_u64 v[216:217], s[0:1], 0, v[190:191]
	ds_read_b128 v[162:165], v241 offset:32768
	ds_read_b128 v[166:169], v241 offset:33792
	ds_read_b128 v[170:173], v241 offset:34816
	ds_read_b128 v[174:177], v241 offset:35840
	ds_read_b128 v[178:181], v241 offset:36864
	ds_read_b128 v[182:185], v241 offset:37888
	ds_read_b128 v[186:189], v241 offset:38912
	ds_read_b128 v[200:203], v241 offset:39936
	global_load_lds_dwordx4 v[216:217], off
	v_lshl_add_u64 v[216:217], s[0:1], 0, v[192:193]
	s_mov_b32 m0, s40
	s_nop 0
	global_load_lds_dwordx4 v[216:217], off
	s_waitcnt vmcnt(8)
	s_waitcnt lgkmcnt(0)
	s_barrier
	v_mfma_f32_16x16x32_bf16 v[142:145], v[114:117], v[162:165], v[142:145]
	s_setprio 1
	v_mfma_f32_16x16x32_bf16 v[138:141], v[126:129], v[162:165], v[138:141]
	v_mfma_f32_16x16x32_bf16 v[110:113], v[114:117], v[170:173], v[110:113]
	v_mfma_f32_16x16x32_bf16 v[106:109], v[126:129], v[170:173], v[106:109]
	v_mfma_f32_16x16x32_bf16 v[94:97], v[114:117], v[178:181], v[94:97]
	v_mfma_f32_16x16x32_bf16 v[90:93], v[126:129], v[178:181], v[90:93]
	v_mfma_f32_16x16x32_bf16 v[78:81], v[114:117], v[186:189], v[78:81]
	v_mfma_f32_16x16x32_bf16 v[74:77], v[126:129], v[186:189], v[74:77]
	v_mfma_f32_16x16x32_bf16 v[142:145], v[122:125], v[166:169], v[142:145]
	v_mfma_f32_16x16x32_bf16 v[138:141], v[134:137], v[166:169], v[138:141]
	v_mfma_f32_16x16x32_bf16 v[110:113], v[122:125], v[174:177], v[110:113]
	v_mfma_f32_16x16x32_bf16 v[106:109], v[134:137], v[174:177], v[106:109]
	v_mfma_f32_16x16x32_bf16 v[94:97], v[122:125], v[182:185], v[94:97]
	v_mfma_f32_16x16x32_bf16 v[90:93], v[134:137], v[182:185], v[90:93]
	v_mfma_f32_16x16x32_bf16 v[78:81], v[122:125], v[200:203], v[78:81]
	v_mfma_f32_16x16x32_bf16 v[74:77], v[134:137], v[200:203], v[74:77]
	s_setprio 0
	s_setprio 1
	v_mfma_f32_16x16x32_bf16 v[130:133], v[146:149], v[162:165], v[130:133]
	v_mfma_f32_16x16x32_bf16 v[118:121], v[154:157], v[162:165], v[118:121]
	v_mfma_f32_16x16x32_bf16 v[102:105], v[146:149], v[170:173], v[102:105]
	v_mfma_f32_16x16x32_bf16 v[98:101], v[154:157], v[170:173], v[98:101]
	v_mfma_f32_16x16x32_bf16 v[86:89], v[146:149], v[178:181], v[86:89]
	v_mfma_f32_16x16x32_bf16 v[82:85], v[154:157], v[178:181], v[82:85]
	v_mfma_f32_16x16x32_bf16 v[70:73], v[146:149], v[186:189], v[70:73]
	v_mfma_f32_16x16x32_bf16 v[66:69], v[154:157], v[186:189], v[66:69]
	v_mfma_f32_16x16x32_bf16 v[130:133], v[150:153], v[166:169], v[130:133]
	v_mfma_f32_16x16x32_bf16 v[118:121], v[158:161], v[166:169], v[118:121]
	v_mfma_f32_16x16x32_bf16 v[102:105], v[150:153], v[174:177], v[102:105]
	v_mfma_f32_16x16x32_bf16 v[98:101], v[158:161], v[174:177], v[98:101]
	v_mfma_f32_16x16x32_bf16 v[86:89], v[150:153], v[182:185], v[86:89]
	v_mfma_f32_16x16x32_bf16 v[82:85], v[158:161], v[182:185], v[82:85]
	v_mfma_f32_16x16x32_bf16 v[70:73], v[150:153], v[200:203], v[70:73]
	v_mfma_f32_16x16x32_bf16 v[66:69], v[158:161], v[200:203], v[66:69]
	s_barrier
	s_setprio 0
	s_add_i32 s0, s39, s18
	v_lshl_add_u64 v[204:205], v[204:205], 0, s[66:67]
	s_mov_b32 m0, s0
	ds_read_b128 v[162:165], v241 offset:49152
	ds_read_b128 v[166:169], v241 offset:50176
	ds_read_b128 v[170:173], v241 offset:51200
	ds_read_b128 v[174:177], v241 offset:52224
	ds_read_b128 v[178:181], v241 offset:53248
	ds_read_b128 v[182:185], v241 offset:54272
	ds_read_b128 v[186:189], v241 offset:55296
	ds_read_b128 v[200:203], v241 offset:56320
	global_load_lds_dwordx4 v[204:205], off
	v_lshl_add_u64 v[204:205], v[206:207], 0, s[66:67]
	s_add_i32 m0, s0, 0x2000
	s_add_i32 s0, s52, s18
	global_load_lds_dwordx4 v[204:205], off
	v_lshl_add_u64 v[204:205], v[208:209], 0, s[66:67]
	s_mov_b32 m0, s0
	s_nop 0
	global_load_lds_dwordx4 v[204:205], off
	v_lshl_add_u64 v[204:205], v[210:211], 0, s[66:67]
	s_add_i32 m0, s0, 0x2000
	s_nop 0
	global_load_lds_dwordx4 v[204:205], off
	v_lshl_add_u64 v[204:205], v[212:213], 0, s[66:67]
	s_mov_b32 m0, s64
	s_nop 0
	global_load_lds_dwordx4 v[204:205], off
	v_lshl_add_u64 v[204:205], v[214:215], 0, s[66:67]
	s_mov_b32 m0, s65
	s_nop 0
	global_load_lds_dwordx4 v[204:205], off
	s_waitcnt vmcnt(8)
	s_waitcnt lgkmcnt(0)
	s_barrier
	v_mfma_f32_16x16x32_bf16 v[62:65], v[114:117], v[162:165], v[62:65]
	s_setprio 1
	v_mfma_f32_16x16x32_bf16 v[58:61], v[126:129], v[162:165], v[58:61]
	v_mfma_f32_16x16x32_bf16 v[46:49], v[114:117], v[170:173], v[46:49]
	v_mfma_f32_16x16x32_bf16 v[42:45], v[126:129], v[170:173], v[42:45]
	v_mfma_f32_16x16x32_bf16 v[30:33], v[114:117], v[178:181], v[30:33]
	v_mfma_f32_16x16x32_bf16 v[26:29], v[126:129], v[178:181], v[26:29]
	v_mfma_f32_16x16x32_bf16 v[14:17], v[114:117], v[186:189], v[14:17]
	v_mfma_f32_16x16x32_bf16 v[10:13], v[126:129], v[186:189], v[10:13]
	v_mfma_f32_16x16x32_bf16 v[62:65], v[122:125], v[166:169], v[62:65]
	v_mfma_f32_16x16x32_bf16 v[58:61], v[134:137], v[166:169], v[58:61]
	v_mfma_f32_16x16x32_bf16 v[46:49], v[122:125], v[174:177], v[46:49]
	v_mfma_f32_16x16x32_bf16 v[42:45], v[134:137], v[174:177], v[42:45]
	v_mfma_f32_16x16x32_bf16 v[30:33], v[122:125], v[182:185], v[30:33]
	v_mfma_f32_16x16x32_bf16 v[26:29], v[134:137], v[182:185], v[26:29]
	v_mfma_f32_16x16x32_bf16 v[14:17], v[122:125], v[200:203], v[14:17]
	v_mfma_f32_16x16x32_bf16 v[10:13], v[134:137], v[200:203], v[10:13]
	s_setprio 0
	s_setprio 1
	v_mfma_f32_16x16x32_bf16 v[54:57], v[146:149], v[162:165], v[54:57]
	v_mfma_f32_16x16x32_bf16 v[50:53], v[154:157], v[162:165], v[50:53]
	v_mfma_f32_16x16x32_bf16 v[38:41], v[146:149], v[170:173], v[38:41]
	v_mfma_f32_16x16x32_bf16 v[34:37], v[154:157], v[170:173], v[34:37]
	v_mfma_f32_16x16x32_bf16 v[22:25], v[146:149], v[178:181], v[22:25]
	v_mfma_f32_16x16x32_bf16 v[18:21], v[154:157], v[178:181], v[18:21]
	v_mfma_f32_16x16x32_bf16 v[6:9], v[146:149], v[186:189], v[6:9]
	v_mfma_f32_16x16x32_bf16 v[2:5], v[154:157], v[186:189], v[2:5]
	v_mfma_f32_16x16x32_bf16 v[54:57], v[150:153], v[166:169], v[54:57]
	v_mfma_f32_16x16x32_bf16 v[50:53], v[158:161], v[166:169], v[50:53]
	v_mfma_f32_16x16x32_bf16 v[38:41], v[150:153], v[174:177], v[38:41]
	v_mfma_f32_16x16x32_bf16 v[34:37], v[158:161], v[174:177], v[34:37]
	v_mfma_f32_16x16x32_bf16 v[22:25], v[150:153], v[182:185], v[22:25]
	v_mfma_f32_16x16x32_bf16 v[18:21], v[158:161], v[182:185], v[18:21]
	v_mfma_f32_16x16x32_bf16 v[6:9], v[150:153], v[200:203], v[6:9]
	v_mfma_f32_16x16x32_bf16 v[2:5], v[158:161], v[200:203], v[2:5]
	s_barrier
	s_setprio 0
	s_add_u32 s2, s2, 0x100
	s_addc_u32 s3, s3, 0
	s_add_u32 s6, s6, 0x100
	s_addc_u32 s7, s7, 0
	s_cmp_ge_u32 s25, s41
	s_mov_b32 s0, s25
	s_cbranch_scc0 .LBB0_519
	v_mov_b32_e32 v242, 0x9000
	v_mov_b32_e32 v244, 0x358637bd
	s_and_b64 vcc, exec, s[30:31]
	s_cbranch_vccz .LBB0_522
	s_barrier

.LBB0_592:
	s_add_i32 s15, s0, 2
	s_add_u32 s25, s2, 0x80
	s_addc_u32 s1, s3, 0
	s_add_i32 s53, 0, 0x10000
	s_cmp_eq_u32 s74, s0
	s_cselect_b32 s1, s37, s1
	s_cselect_b32 s0, s36, s25
	s_cselect_b32 s65, s39, s7
	s_cselect_b32 s64, s38, s6
	s_add_i32 s25, 0, 0x14000
	v_add_u32_e32 v142, s53, v190
	v_add_u32_e32 v168, s25, v190
	ds_read_b128 v[130:133], v142
	ds_read_b128 v[134:137], v142 offset:1024
	ds_read_b128 v[138:141], v142 offset:2048
	ds_read_b128 v[142:145], v142 offset:3072
	ds_read_b128 v[156:159], v168
	ds_read_b128 v[160:163], v168 offset:1024
	ds_read_b128 v[164:167], v168 offset:2048
	ds_read_b128 v[168:171], v168 offset:3072
	v_lshl_add_u64 v[208:209], s[2:3], 0, v[152:153]
	s_add_i32 m0, s19, 0xc000
	ds_read_b128 v[172:175], v191
	ds_read_b128 v[176:179], v191 offset:1024
	ds_read_b128 v[180:183], v191 offset:2048
	ds_read_b128 v[184:187], v191 offset:3072
	ds_read_b128 v[192:195], v191 offset:4096
	ds_read_b128 v[196:199], v191 offset:5120
	ds_read_b128 v[200:203], v191 offset:6144
	ds_read_b128 v[204:207], v191 offset:7168
	global_load_lds_dwordx4 v[208:209], off
	v_lshl_add_u64 v[208:209], s[2:3], 0, v[154:155]
	s_add_i32 m0, s19, 0xe000
	s_nop 0
	global_load_lds_dwordx4 v[208:209], off
	s_waitcnt vmcnt(8)
	s_waitcnt lgkmcnt(0)
	s_barrier
	v_mfma_f32_16x16x32_bf16 v[126:129], v[130:133], v[172:175], v[126:129]
	s_setprio 1
	v_mfma_f32_16x16x32_bf16 v[122:125], v[138:141], v[172:175], v[122:125]
	v_mfma_f32_16x16x32_bf16 v[110:113], v[130:133], v[180:183], v[110:113]
	v_mfma_f32_16x16x32_bf16 v[106:109], v[138:141], v[180:183], v[106:109]
	v_mfma_f32_16x16x32_bf16 v[94:97], v[130:133], v[192:195], v[94:97]
	v_mfma_f32_16x16x32_bf16 v[90:93], v[138:141], v[192:195], v[90:93]
	v_mfma_f32_16x16x32_bf16 v[78:81], v[130:133], v[200:203], v[78:81]
	v_mfma_f32_16x16x32_bf16 v[74:77], v[138:141], v[200:203], v[74:77]
	v_mfma_f32_16x16x32_bf16 v[126:129], v[134:137], v[176:179], v[126:129]
	v_mfma_f32_16x16x32_bf16 v[122:125], v[142:145], v[176:179], v[122:125]
	v_mfma_f32_16x16x32_bf16 v[110:113], v[134:137], v[184:187], v[110:113]
	v_mfma_f32_16x16x32_bf16 v[106:109], v[142:145], v[184:187], v[106:109]
	v_mfma_f32_16x16x32_bf16 v[94:97], v[134:137], v[196:199], v[94:97]
	v_mfma_f32_16x16x32_bf16 v[90:93], v[142:145], v[196:199], v[90:93]
	v_mfma_f32_16x16x32_bf16 v[78:81], v[134:137], v[204:207], v[78:81]
	v_mfma_f32_16x16x32_bf16 v[74:77], v[142:145], v[204:207], v[74:77]
	s_setprio 0
	s_setprio 1
	v_mfma_f32_16x16x32_bf16 v[118:121], v[156:159], v[172:175], v[118:121]
	v_mfma_f32_16x16x32_bf16 v[114:117], v[164:167], v[172:175], v[114:117]
	v_mfma_f32_16x16x32_bf16 v[102:105], v[156:159], v[180:183], v[102:105]
	v_mfma_f32_16x16x32_bf16 v[98:101], v[164:167], v[180:183], v[98:101]
	v_mfma_f32_16x16x32_bf16 v[86:89], v[156:159], v[192:195], v[86:89]
	v_mfma_f32_16x16x32_bf16 v[82:85], v[164:167], v[192:195], v[82:85]
	v_mfma_f32_16x16x32_bf16 v[70:73], v[156:159], v[200:203], v[70:73]
	v_mfma_f32_16x16x32_bf16 v[66:69], v[164:167], v[200:203], v[66:69]
	v_mfma_f32_16x16x32_bf16 v[118:121], v[160:163], v[176:179], v[118:121]
	v_mfma_f32_16x16x32_bf16 v[114:117], v[168:171], v[176:179], v[114:117]
	v_mfma_f32_16x16x32_bf16 v[102:105], v[160:163], v[184:187], v[102:105]
	v_mfma_f32_16x16x32_bf16 v[98:101], v[168:171], v[184:187], v[98:101]
	v_mfma_f32_16x16x32_bf16 v[86:89], v[160:163], v[196:199], v[86:89]
	v_mfma_f32_16x16x32_bf16 v[82:85], v[168:171], v[196:199], v[82:85]
	v_mfma_f32_16x16x32_bf16 v[70:73], v[160:163], v[204:207], v[70:73]
	v_mfma_f32_16x16x32_bf16 v[66:69], v[168:171], v[204:207], v[66:69]
	s_barrier
	s_setprio 0
	s_add_i32 s53, s53, s18
	v_lshl_add_u64 v[208:209], s[64:65], 0, v[0:1]
	s_mov_b32 m0, s53
	ds_read_b128 v[172:175], v191 offset:16384
	ds_read_b128 v[176:179], v191 offset:17408
	ds_read_b128 v[180:183], v191 offset:18432
	ds_read_b128 v[184:187], v191 offset:19456
	ds_read_b128 v[192:195], v191 offset:20480
	ds_read_b128 v[196:199], v191 offset:21504
	ds_read_b128 v[200:203], v191 offset:22528
	ds_read_b128 v[204:207], v191 offset:23552
	global_load_lds_dwordx4 v[208:209], off
	s_add_i32 m0, s53, 0x2000
	v_lshl_add_u64 v[210:211], s[64:65], 0, v[150:151]
	s_add_u32 s64, s64, s50
	s_addc_u32 s65, s65, 0
	s_add_i32 s25, s25, s18
	global_load_lds_dwordx4 v[210:211], off
	v_lshl_add_u64 v[212:213], s[64:65], 0, v[0:1]
	s_mov_b32 m0, s25
	v_lshl_add_u64 v[214:215], s[64:65], 0, v[150:151]
	global_load_lds_dwordx4 v[212:213], off
	s_add_i32 m0, s25, 0x2000
	v_lshl_add_u64 v[216:217], s[0:1], 0, v[146:147]
	global_load_lds_dwordx4 v[214:215], off
	s_mov_b32 m0, s19
	v_lshl_add_u64 v[218:219], s[0:1], 0, v[148:149]
	global_load_lds_dwordx4 v[216:217], off
	s_mov_b32 m0, s22
	s_nop 0
	global_load_lds_dwordx4 v[218:219], off
	s_waitcnt vmcnt(8)
	s_waitcnt lgkmcnt(0)
	s_barrier
	v_mfma_f32_16x16x32_bf16 v[62:65], v[130:133], v[172:175], v[62:65]
	s_setprio 1
	v_mfma_f32_16x16x32_bf16 v[58:61], v[138:141], v[172:175], v[58:61]
	v_mfma_f32_16x16x32_bf16 v[46:49], v[130:133], v[180:183], v[46:49]
	v_mfma_f32_16x16x32_bf16 v[42:45], v[138:141], v[180:183], v[42:45]
	v_mfma_f32_16x16x32_bf16 v[30:33], v[130:133], v[192:195], v[30:33]
	v_mfma_f32_16x16x32_bf16 v[26:29], v[138:141], v[192:195], v[26:29]
	v_mfma_f32_16x16x32_bf16 v[14:17], v[130:133], v[200:203], v[14:17]
	v_mfma_f32_16x16x32_bf16 v[10:13], v[138:141], v[200:203], v[10:13]
	v_mfma_f32_16x16x32_bf16 v[62:65], v[134:137], v[176:179], v[62:65]
	v_mfma_f32_16x16x32_bf16 v[58:61], v[142:145], v[176:179], v[58:61]
	v_mfma_f32_16x16x32_bf16 v[46:49], v[134:137], v[184:187], v[46:49]
	v_mfma_f32_16x16x32_bf16 v[42:45], v[142:145], v[184:187], v[42:45]
	v_mfma_f32_16x16x32_bf16 v[30:33], v[134:137], v[196:199], v[30:33]
	v_mfma_f32_16x16x32_bf16 v[26:29], v[142:145], v[196:199], v[26:29]
	v_mfma_f32_16x16x32_bf16 v[14:17], v[134:137], v[204:207], v[14:17]
	v_mfma_f32_16x16x32_bf16 v[10:13], v[142:145], v[204:207], v[10:13]
	s_setprio 0
	s_setprio 1
	v_mfma_f32_16x16x32_bf16 v[54:57], v[156:159], v[172:175], v[54:57]
	v_mfma_f32_16x16x32_bf16 v[50:53], v[164:167], v[172:175], v[50:53]
	v_mfma_f32_16x16x32_bf16 v[38:41], v[156:159], v[180:183], v[38:41]
	v_mfma_f32_16x16x32_bf16 v[34:37], v[164:167], v[180:183], v[34:37]
	v_mfma_f32_16x16x32_bf16 v[22:25], v[156:159], v[192:195], v[22:25]
	v_mfma_f32_16x16x32_bf16 v[18:21], v[164:167], v[192:195], v[18:21]
	v_mfma_f32_16x16x32_bf16 v[6:9], v[156:159], v[200:203], v[6:9]
	v_mfma_f32_16x16x32_bf16 v[2:5], v[164:167], v[200:203], v[2:5]
	v_mfma_f32_16x16x32_bf16 v[54:57], v[160:163], v[176:179], v[54:57]
	v_mfma_f32_16x16x32_bf16 v[50:53], v[168:171], v[176:179], v[50:53]
	v_mfma_f32_16x16x32_bf16 v[38:41], v[160:163], v[184:187], v[38:41]
	v_mfma_f32_16x16x32_bf16 v[34:37], v[168:171], v[184:187], v[34:37]
	v_mfma_f32_16x16x32_bf16 v[22:25], v[160:163], v[196:199], v[22:25]
	v_mfma_f32_16x16x32_bf16 v[18:21], v[168:171], v[196:199], v[18:21]
	v_mfma_f32_16x16x32_bf16 v[6:9], v[160:163], v[204:207], v[6:9]
	v_mfma_f32_16x16x32_bf16 v[2:5], v[168:171], v[204:207], v[2:5]
	s_barrier
	s_setprio 0
	s_add_i32 s25, 0, 0x18000
	s_add_i32 s53, 0, 0x1c000
	v_add_u32_e32 v142, s25, v190
	v_add_u32_e32 v168, s53, v190
	ds_read_b128 v[130:133], v142
	ds_read_b128 v[134:137], v142 offset:1024
	ds_read_b128 v[138:141], v142 offset:2048
	ds_read_b128 v[142:145], v142 offset:3072
	ds_read_b128 v[156:159], v168
	ds_read_b128 v[160:163], v168 offset:1024
	ds_read_b128 v[164:167], v168 offset:2048
	ds_read_b128 v[168:171], v168 offset:3072
	s_add_u32 s0, s0, s50
	s_addc_u32 s1, s1, 0
	s_mov_b32 m0, s23
	v_lshl_add_u64 v[220:221], s[0:1], 0, v[146:147]
	ds_read_b128 v[172:175], v191 offset:32768
	ds_read_b128 v[176:179], v191 offset:33792
	ds_read_b128 v[180:183], v191 offset:34816
	ds_read_b128 v[184:187], v191 offset:35840
	ds_read_b128 v[192:195], v191 offset:36864
	ds_read_b128 v[196:199], v191 offset:37888
	ds_read_b128 v[200:203], v191 offset:38912
	ds_read_b128 v[204:207], v191 offset:39936
	global_load_lds_dwordx4 v[220:221], off
	v_lshl_add_u64 v[220:221], s[0:1], 0, v[148:149]
	s_mov_b32 m0, s40
	s_nop 0
	global_load_lds_dwordx4 v[220:221], off
	s_waitcnt vmcnt(8)
	s_waitcnt lgkmcnt(0)
	s_barrier
	v_mfma_f32_16x16x32_bf16 v[126:129], v[130:133], v[172:175], v[126:129]
	s_setprio 1
	v_mfma_f32_16x16x32_bf16 v[122:125], v[138:141], v[172:175], v[122:125]
	v_mfma_f32_16x16x32_bf16 v[110:113], v[130:133], v[180:183], v[110:113]
	v_mfma_f32_16x16x32_bf16 v[106:109], v[138:141], v[180:183], v[106:109]
	v_mfma_f32_16x16x32_bf16 v[94:97], v[130:133], v[192:195], v[94:97]
	v_mfma_f32_16x16x32_bf16 v[90:93], v[138:141], v[192:195], v[90:93]
	v_mfma_f32_16x16x32_bf16 v[78:81], v[130:133], v[200:203], v[78:81]
	v_mfma_f32_16x16x32_bf16 v[74:77], v[138:141], v[200:203], v[74:77]
	v_mfma_f32_16x16x32_bf16 v[126:129], v[134:137], v[176:179], v[126:129]
	v_mfma_f32_16x16x32_bf16 v[122:125], v[142:145], v[176:179], v[122:125]
	v_mfma_f32_16x16x32_bf16 v[110:113], v[134:137], v[184:187], v[110:113]
	v_mfma_f32_16x16x32_bf16 v[106:109], v[142:145], v[184:187], v[106:109]
	v_mfma_f32_16x16x32_bf16 v[94:97], v[134:137], v[196:199], v[94:97]
	v_mfma_f32_16x16x32_bf16 v[90:93], v[142:145], v[196:199], v[90:93]
	v_mfma_f32_16x16x32_bf16 v[78:81], v[134:137], v[204:207], v[78:81]
	v_mfma_f32_16x16x32_bf16 v[74:77], v[142:145], v[204:207], v[74:77]
	s_setprio 0
	s_setprio 1
	v_mfma_f32_16x16x32_bf16 v[118:121], v[156:159], v[172:175], v[118:121]
	v_mfma_f32_16x16x32_bf16 v[114:117], v[164:167], v[172:175], v[114:117]
	v_mfma_f32_16x16x32_bf16 v[102:105], v[156:159], v[180:183], v[102:105]
	v_mfma_f32_16x16x32_bf16 v[98:101], v[164:167], v[180:183], v[98:101]
	v_mfma_f32_16x16x32_bf16 v[86:89], v[156:159], v[192:195], v[86:89]
	v_mfma_f32_16x16x32_bf16 v[82:85], v[164:167], v[192:195], v[82:85]
	v_mfma_f32_16x16x32_bf16 v[70:73], v[156:159], v[200:203], v[70:73]
	v_mfma_f32_16x16x32_bf16 v[66:69], v[164:167], v[200:203], v[66:69]
	v_mfma_f32_16x16x32_bf16 v[118:121], v[160:163], v[176:179], v[118:121]
	v_mfma_f32_16x16x32_bf16 v[114:117], v[168:171], v[176:179], v[114:117]
	v_mfma_f32_16x16x32_bf16 v[102:105], v[160:163], v[184:187], v[102:105]
	v_mfma_f32_16x16x32_bf16 v[98:101], v[168:171], v[184:187], v[98:101]
	v_mfma_f32_16x16x32_bf16 v[86:89], v[160:163], v[196:199], v[86:89]
	v_mfma_f32_16x16x32_bf16 v[82:85], v[168:171], v[196:199], v[82:85]
	v_mfma_f32_16x16x32_bf16 v[70:73], v[160:163], v[204:207], v[70:73]
	v_mfma_f32_16x16x32_bf16 v[66:69], v[168:171], v[204:207], v[66:69]
	s_barrier
	s_setprio 0
	s_add_i32 s0, s25, s18
	v_lshl_add_u64 v[208:209], v[208:209], 0, s[66:67]
	s_mov_b32 m0, s0
	ds_read_b128 v[172:175], v191 offset:49152
	ds_read_b128 v[176:179], v191 offset:50176
	ds_read_b128 v[180:183], v191 offset:51200
	ds_read_b128 v[184:187], v191 offset:52224
	ds_read_b128 v[192:195], v191 offset:53248
	ds_read_b128 v[196:199], v191 offset:54272
	ds_read_b128 v[200:203], v191 offset:55296
	ds_read_b128 v[204:207], v191 offset:56320
	global_load_lds_dwordx4 v[208:209], off
	v_lshl_add_u64 v[208:209], v[210:211], 0, s[66:67]
	s_add_i32 m0, s0, 0x2000
	s_add_i32 s0, s53, s18
	global_load_lds_dwordx4 v[208:209], off
	v_lshl_add_u64 v[208:209], v[212:213], 0, s[66:67]
	s_mov_b32 m0, s0
	s_nop 0
	global_load_lds_dwordx4 v[208:209], off
	v_lshl_add_u64 v[208:209], v[214:215], 0, s[66:67]
	s_add_i32 m0, s0, 0x2000
	s_nop 0
	global_load_lds_dwordx4 v[208:209], off
	v_lshl_add_u64 v[208:209], v[216:217], 0, s[66:67]
	s_mov_b32 m0, s68
	s_nop 0
	global_load_lds_dwordx4 v[208:209], off
	v_lshl_add_u64 v[208:209], v[218:219], 0, s[66:67]
	s_mov_b32 m0, s69
	s_nop 0
	global_load_lds_dwordx4 v[208:209], off
	s_waitcnt vmcnt(8)
	s_waitcnt lgkmcnt(0)
	s_barrier
	v_mfma_f32_16x16x32_bf16 v[62:65], v[130:133], v[172:175], v[62:65]
	s_setprio 1
	v_mfma_f32_16x16x32_bf16 v[58:61], v[138:141], v[172:175], v[58:61]
	v_mfma_f32_16x16x32_bf16 v[46:49], v[130:133], v[180:183], v[46:49]
	v_mfma_f32_16x16x32_bf16 v[42:45], v[138:141], v[180:183], v[42:45]
	v_mfma_f32_16x16x32_bf16 v[30:33], v[130:133], v[192:195], v[30:33]
	v_mfma_f32_16x16x32_bf16 v[26:29], v[138:141], v[192:195], v[26:29]
	v_mfma_f32_16x16x32_bf16 v[14:17], v[130:133], v[200:203], v[14:17]
	v_mfma_f32_16x16x32_bf16 v[10:13], v[138:141], v[200:203], v[10:13]
	v_mfma_f32_16x16x32_bf16 v[62:65], v[134:137], v[176:179], v[62:65]
	v_mfma_f32_16x16x32_bf16 v[58:61], v[142:145], v[176:179], v[58:61]
	v_mfma_f32_16x16x32_bf16 v[46:49], v[134:137], v[184:187], v[46:49]
	v_mfma_f32_16x16x32_bf16 v[42:45], v[142:145], v[184:187], v[42:45]
	v_mfma_f32_16x16x32_bf16 v[30:33], v[134:137], v[196:199], v[30:33]
	v_mfma_f32_16x16x32_bf16 v[26:29], v[142:145], v[196:199], v[26:29]
	v_mfma_f32_16x16x32_bf16 v[14:17], v[134:137], v[204:207], v[14:17]
	v_mfma_f32_16x16x32_bf16 v[10:13], v[142:145], v[204:207], v[10:13]
	s_setprio 0
	s_setprio 1
	v_mfma_f32_16x16x32_bf16 v[54:57], v[156:159], v[172:175], v[54:57]
	v_mfma_f32_16x16x32_bf16 v[50:53], v[164:167], v[172:175], v[50:53]
	v_mfma_f32_16x16x32_bf16 v[38:41], v[156:159], v[180:183], v[38:41]
	v_mfma_f32_16x16x32_bf16 v[34:37], v[164:167], v[180:183], v[34:37]
	v_mfma_f32_16x16x32_bf16 v[22:25], v[156:159], v[192:195], v[22:25]
	v_mfma_f32_16x16x32_bf16 v[18:21], v[164:167], v[192:195], v[18:21]
	v_mfma_f32_16x16x32_bf16 v[6:9], v[156:159], v[200:203], v[6:9]
	v_mfma_f32_16x16x32_bf16 v[2:5], v[164:167], v[200:203], v[2:5]
	v_mfma_f32_16x16x32_bf16 v[54:57], v[160:163], v[176:179], v[54:57]
	v_mfma_f32_16x16x32_bf16 v[50:53], v[168:171], v[176:179], v[50:53]
	v_mfma_f32_16x16x32_bf16 v[38:41], v[160:163], v[184:187], v[38:41]
	v_mfma_f32_16x16x32_bf16 v[34:37], v[168:171], v[184:187], v[34:37]
	v_mfma_f32_16x16x32_bf16 v[22:25], v[160:163], v[196:199], v[22:25]
	v_mfma_f32_16x16x32_bf16 v[18:21], v[168:171], v[196:199], v[18:21]
	v_mfma_f32_16x16x32_bf16 v[6:9], v[160:163], v[204:207], v[6:9]
	v_mfma_f32_16x16x32_bf16 v[2:5], v[168:171], v[204:207], v[2:5]
	s_barrier
	s_setprio 0
	s_add_u32 s2, s2, 0x100
	s_addc_u32 s3, s3, 0
	s_add_u32 s6, s6, 0x100
	s_addc_u32 s7, s7, 0
	s_cmp_ge_u32 s15, s41
	s_mov_b32 s0, s15
	s_cbranch_scc0 .LBB0_592
	s_and_b64 vcc, exec, s[30:31]
	s_cbranch_vccz .LBB0_595
	s_barrier

.LBB0_647:
	s_add_i32 s69, s0, 2
	s_add_u32 s74, s2, 0x80
	s_addc_u32 s1, s3, 0
	s_add_i32 s78, 0, 0x10000
	s_cmp_eq_u32 s41, s0
	s_cselect_b32 s1, s7, s1
	s_cselect_b32 s0, s6, s74
	s_cselect_b32 s75, s35, s68
	s_cselect_b32 s74, s34, s65
	s_add_i32 s79, 0, 0x14000
	v_add_u32_e32 v134, s78, v239
	v_add_u32_e32 v158, s79, v239
	ds_read_b128 v[122:125], v134
	ds_read_b128 v[126:129], v134 offset:1024
	ds_read_b128 v[130:133], v134 offset:2048
	ds_read_b128 v[134:137], v134 offset:3072
	ds_read_b128 v[138:141], v158
	ds_read_b128 v[142:145], v158 offset:1024
	ds_read_b128 v[146:149], v158 offset:2048
	ds_read_b128 v[158:161], v158 offset:3072
	v_lshl_add_u64 v[204:205], s[2:3], 0, v[196:197]
	s_add_i32 m0, s28, 0xc000
	ds_read_b128 v[162:165], v241
	ds_read_b128 v[166:169], v241 offset:1024
	ds_read_b128 v[170:173], v241 offset:2048
	ds_read_b128 v[174:177], v241 offset:3072
	ds_read_b128 v[178:181], v241 offset:4096
	ds_read_b128 v[182:185], v241 offset:5120
	ds_read_b128 v[186:189], v241 offset:6144
	ds_read_b128 v[200:203], v241 offset:7168
	global_load_lds_dwordx4 v[204:205], off
	v_lshl_add_u64 v[204:205], s[2:3], 0, v[198:199]
	s_add_i32 m0, s28, 0xe000
	s_nop 0
	global_load_lds_dwordx4 v[204:205], off
	s_waitcnt vmcnt(8)
	s_waitcnt lgkmcnt(0)
	s_barrier
	v_mfma_f32_16x16x32_bf16 v[154:157], v[122:125], v[162:165], v[154:157]
	s_setprio 1
	v_mfma_f32_16x16x32_bf16 v[150:153], v[130:133], v[162:165], v[150:153]
	v_mfma_f32_16x16x32_bf16 v[114:117], v[122:125], v[170:173], v[114:117]
	v_mfma_f32_16x16x32_bf16 v[106:109], v[130:133], v[170:173], v[106:109]
	v_mfma_f32_16x16x32_bf16 v[98:101], v[122:125], v[178:181], v[98:101]
	v_mfma_f32_16x16x32_bf16 v[90:93], v[130:133], v[178:181], v[90:93]
	v_mfma_f32_16x16x32_bf16 v[82:85], v[122:125], v[186:189], v[82:85]
	v_mfma_f32_16x16x32_bf16 v[74:77], v[130:133], v[186:189], v[74:77]
	v_mfma_f32_16x16x32_bf16 v[154:157], v[126:129], v[166:169], v[154:157]
	v_mfma_f32_16x16x32_bf16 v[150:153], v[134:137], v[166:169], v[150:153]
	v_mfma_f32_16x16x32_bf16 v[114:117], v[126:129], v[174:177], v[114:117]
	v_mfma_f32_16x16x32_bf16 v[106:109], v[134:137], v[174:177], v[106:109]
	v_mfma_f32_16x16x32_bf16 v[98:101], v[126:129], v[182:185], v[98:101]
	v_mfma_f32_16x16x32_bf16 v[90:93], v[134:137], v[182:185], v[90:93]
	v_mfma_f32_16x16x32_bf16 v[82:85], v[126:129], v[200:203], v[82:85]
	v_mfma_f32_16x16x32_bf16 v[74:77], v[134:137], v[200:203], v[74:77]
	s_setprio 0
	s_setprio 1
	v_mfma_f32_16x16x32_bf16 v[118:121], v[138:141], v[162:165], v[118:121]
	v_mfma_f32_16x16x32_bf16 v[110:113], v[146:149], v[162:165], v[110:113]
	v_mfma_f32_16x16x32_bf16 v[102:105], v[138:141], v[170:173], v[102:105]
	v_mfma_f32_16x16x32_bf16 v[94:97], v[146:149], v[170:173], v[94:97]
	v_mfma_f32_16x16x32_bf16 v[86:89], v[138:141], v[178:181], v[86:89]
	v_mfma_f32_16x16x32_bf16 v[78:81], v[146:149], v[178:181], v[78:81]
	v_mfma_f32_16x16x32_bf16 v[70:73], v[138:141], v[186:189], v[70:73]
	v_mfma_f32_16x16x32_bf16 v[66:69], v[146:149], v[186:189], v[66:69]
	v_mfma_f32_16x16x32_bf16 v[118:121], v[142:145], v[166:169], v[118:121]
	v_mfma_f32_16x16x32_bf16 v[110:113], v[158:161], v[166:169], v[110:113]
	v_mfma_f32_16x16x32_bf16 v[102:105], v[142:145], v[174:177], v[102:105]
	v_mfma_f32_16x16x32_bf16 v[94:97], v[158:161], v[174:177], v[94:97]
	v_mfma_f32_16x16x32_bf16 v[86:89], v[142:145], v[182:185], v[86:89]
	v_mfma_f32_16x16x32_bf16 v[78:81], v[158:161], v[182:185], v[78:81]
	v_mfma_f32_16x16x32_bf16 v[70:73], v[142:145], v[200:203], v[70:73]
	v_mfma_f32_16x16x32_bf16 v[66:69], v[158:161], v[200:203], v[66:69]
	s_barrier
	s_setprio 0
	s_add_i32 s78, s78, s14
	v_lshl_add_u64 v[204:205], s[74:75], 0, v[0:1]
	s_mov_b32 m0, s78
	ds_read_b128 v[162:165], v241 offset:16384
	ds_read_b128 v[166:169], v241 offset:17408
	ds_read_b128 v[170:173], v241 offset:18432
	ds_read_b128 v[174:177], v241 offset:19456
	ds_read_b128 v[178:181], v241 offset:20480
	ds_read_b128 v[182:185], v241 offset:21504
	ds_read_b128 v[186:189], v241 offset:22528
	ds_read_b128 v[200:203], v241 offset:23552
	global_load_lds_dwordx4 v[204:205], off
	s_add_i32 m0, s78, 0x2000
	v_lshl_add_u64 v[206:207], s[74:75], 0, v[190:191]
	s_add_u32 s74, s74, s50
	s_addc_u32 s75, s75, 0
	s_add_i32 s78, s79, s14
	global_load_lds_dwordx4 v[206:207], off
	v_lshl_add_u64 v[208:209], s[74:75], 0, v[0:1]
	s_mov_b32 m0, s78
	v_lshl_add_u64 v[210:211], s[74:75], 0, v[190:191]
	global_load_lds_dwordx4 v[208:209], off
	s_add_i32 m0, s78, 0x2000
	v_lshl_add_u64 v[212:213], s[0:1], 0, v[194:195]
	global_load_lds_dwordx4 v[210:211], off
	s_mov_b32 m0, s28
	v_lshl_add_u64 v[214:215], s[0:1], 0, v[192:193]
	global_load_lds_dwordx4 v[212:213], off
	s_mov_b32 m0, s29
	s_nop 0
	global_load_lds_dwordx4 v[214:215], off
	s_waitcnt vmcnt(8)
	s_waitcnt lgkmcnt(0)
	s_barrier
	v_mfma_f32_16x16x32_bf16 v[62:65], v[122:125], v[162:165], v[62:65]
	s_setprio 1
	v_mfma_f32_16x16x32_bf16 v[58:61], v[130:133], v[162:165], v[58:61]
	v_mfma_f32_16x16x32_bf16 v[50:53], v[122:125], v[170:173], v[50:53]
	v_mfma_f32_16x16x32_bf16 v[42:45], v[130:133], v[170:173], v[42:45]
	v_mfma_f32_16x16x32_bf16 v[34:37], v[122:125], v[178:181], v[34:37]
	v_mfma_f32_16x16x32_bf16 v[26:29], v[130:133], v[178:181], v[26:29]
	v_mfma_f32_16x16x32_bf16 v[18:21], v[122:125], v[186:189], v[18:21]
	v_mfma_f32_16x16x32_bf16 v[10:13], v[130:133], v[186:189], v[10:13]
	v_mfma_f32_16x16x32_bf16 v[62:65], v[126:129], v[166:169], v[62:65]
	v_mfma_f32_16x16x32_bf16 v[58:61], v[134:137], v[166:169], v[58:61]
	v_mfma_f32_16x16x32_bf16 v[50:53], v[126:129], v[174:177], v[50:53]
	v_mfma_f32_16x16x32_bf16 v[42:45], v[134:137], v[174:177], v[42:45]
	v_mfma_f32_16x16x32_bf16 v[34:37], v[126:129], v[182:185], v[34:37]
	v_mfma_f32_16x16x32_bf16 v[26:29], v[134:137], v[182:185], v[26:29]
	v_mfma_f32_16x16x32_bf16 v[18:21], v[126:129], v[200:203], v[18:21]
	v_mfma_f32_16x16x32_bf16 v[10:13], v[134:137], v[200:203], v[10:13]
	s_setprio 0
	s_setprio 1
	v_mfma_f32_16x16x32_bf16 v[54:57], v[138:141], v[162:165], v[54:57]
	v_mfma_f32_16x16x32_bf16 v[46:49], v[146:149], v[162:165], v[46:49]
	v_mfma_f32_16x16x32_bf16 v[38:41], v[138:141], v[170:173], v[38:41]
	v_mfma_f32_16x16x32_bf16 v[30:33], v[146:149], v[170:173], v[30:33]
	v_mfma_f32_16x16x32_bf16 v[22:25], v[138:141], v[178:181], v[22:25]
	v_mfma_f32_16x16x32_bf16 v[14:17], v[146:149], v[178:181], v[14:17]
	v_mfma_f32_16x16x32_bf16 v[6:9], v[138:141], v[186:189], v[6:9]
	v_mfma_f32_16x16x32_bf16 v[2:5], v[146:149], v[186:189], v[2:5]
	v_mfma_f32_16x16x32_bf16 v[54:57], v[142:145], v[166:169], v[54:57]
	v_mfma_f32_16x16x32_bf16 v[46:49], v[158:161], v[166:169], v[46:49]
	v_mfma_f32_16x16x32_bf16 v[38:41], v[142:145], v[174:177], v[38:41]
	v_mfma_f32_16x16x32_bf16 v[30:33], v[158:161], v[174:177], v[30:33]
	v_mfma_f32_16x16x32_bf16 v[22:25], v[142:145], v[182:185], v[22:25]
	v_mfma_f32_16x16x32_bf16 v[14:17], v[158:161], v[182:185], v[14:17]
	v_mfma_f32_16x16x32_bf16 v[6:9], v[142:145], v[200:203], v[6:9]
	v_mfma_f32_16x16x32_bf16 v[2:5], v[158:161], v[200:203], v[2:5]
	s_barrier
	s_setprio 0
	s_add_i32 s74, 0, 0x18000
	s_add_i32 s75, 0, 0x1c000
	v_add_u32_e32 v134, s74, v239
	v_add_u32_e32 v158, s75, v239
	ds_read_b128 v[122:125], v134
	ds_read_b128 v[126:129], v134 offset:1024
	ds_read_b128 v[130:133], v134 offset:2048
	ds_read_b128 v[134:137], v134 offset:3072
	ds_read_b128 v[138:141], v158
	ds_read_b128 v[142:145], v158 offset:1024
	ds_read_b128 v[146:149], v158 offset:2048
	ds_read_b128 v[158:161], v158 offset:3072
	s_add_u32 s0, s0, s50
	s_addc_u32 s1, s1, 0
	s_mov_b32 m0, s36
	v_lshl_add_u64 v[216:217], s[0:1], 0, v[194:195]
	ds_read_b128 v[162:165], v241 offset:32768
	ds_read_b128 v[166:169], v241 offset:33792
	ds_read_b128 v[170:173], v241 offset:34816
	ds_read_b128 v[174:177], v241 offset:35840
	ds_read_b128 v[178:181], v241 offset:36864
	ds_read_b128 v[182:185], v241 offset:37888
	ds_read_b128 v[186:189], v241 offset:38912
	ds_read_b128 v[200:203], v241 offset:39936
	global_load_lds_dwordx4 v[216:217], off
	v_lshl_add_u64 v[216:217], s[0:1], 0, v[192:193]
	s_mov_b32 m0, s37
	s_nop 0
	global_load_lds_dwordx4 v[216:217], off
	s_waitcnt vmcnt(8)
	s_waitcnt lgkmcnt(0)
	s_barrier
	v_mfma_f32_16x16x32_bf16 v[154:157], v[122:125], v[162:165], v[154:157]
	s_setprio 1
	v_mfma_f32_16x16x32_bf16 v[150:153], v[130:133], v[162:165], v[150:153]
	v_mfma_f32_16x16x32_bf16 v[114:117], v[122:125], v[170:173], v[114:117]
	v_mfma_f32_16x16x32_bf16 v[106:109], v[130:133], v[170:173], v[106:109]
	v_mfma_f32_16x16x32_bf16 v[98:101], v[122:125], v[178:181], v[98:101]
	v_mfma_f32_16x16x32_bf16 v[90:93], v[130:133], v[178:181], v[90:93]
	v_mfma_f32_16x16x32_bf16 v[82:85], v[122:125], v[186:189], v[82:85]
	v_mfma_f32_16x16x32_bf16 v[74:77], v[130:133], v[186:189], v[74:77]
	v_mfma_f32_16x16x32_bf16 v[154:157], v[126:129], v[166:169], v[154:157]
	v_mfma_f32_16x16x32_bf16 v[150:153], v[134:137], v[166:169], v[150:153]
	v_mfma_f32_16x16x32_bf16 v[114:117], v[126:129], v[174:177], v[114:117]
	v_mfma_f32_16x16x32_bf16 v[106:109], v[134:137], v[174:177], v[106:109]
	v_mfma_f32_16x16x32_bf16 v[98:101], v[126:129], v[182:185], v[98:101]
	v_mfma_f32_16x16x32_bf16 v[90:93], v[134:137], v[182:185], v[90:93]
	v_mfma_f32_16x16x32_bf16 v[82:85], v[126:129], v[200:203], v[82:85]
	v_mfma_f32_16x16x32_bf16 v[74:77], v[134:137], v[200:203], v[74:77]
	s_setprio 0
	s_setprio 1
	v_mfma_f32_16x16x32_bf16 v[118:121], v[138:141], v[162:165], v[118:121]
	v_mfma_f32_16x16x32_bf16 v[110:113], v[146:149], v[162:165], v[110:113]
	v_mfma_f32_16x16x32_bf16 v[102:105], v[138:141], v[170:173], v[102:105]
	v_mfma_f32_16x16x32_bf16 v[94:97], v[146:149], v[170:173], v[94:97]
	v_mfma_f32_16x16x32_bf16 v[86:89], v[138:141], v[178:181], v[86:89]
	v_mfma_f32_16x16x32_bf16 v[78:81], v[146:149], v[178:181], v[78:81]
	v_mfma_f32_16x16x32_bf16 v[70:73], v[138:141], v[186:189], v[70:73]
	v_mfma_f32_16x16x32_bf16 v[66:69], v[146:149], v[186:189], v[66:69]
	v_mfma_f32_16x16x32_bf16 v[118:121], v[142:145], v[166:169], v[118:121]
	v_mfma_f32_16x16x32_bf16 v[110:113], v[158:161], v[166:169], v[110:113]
	v_mfma_f32_16x16x32_bf16 v[102:105], v[142:145], v[174:177], v[102:105]
	v_mfma_f32_16x16x32_bf16 v[94:97], v[158:161], v[174:177], v[94:97]
	v_mfma_f32_16x16x32_bf16 v[86:89], v[142:145], v[182:185], v[86:89]
	v_mfma_f32_16x16x32_bf16 v[78:81], v[158:161], v[182:185], v[78:81]
	v_mfma_f32_16x16x32_bf16 v[70:73], v[142:145], v[200:203], v[70:73]
	v_mfma_f32_16x16x32_bf16 v[66:69], v[158:161], v[200:203], v[66:69]
	s_barrier
	s_setprio 0
	s_add_i32 s0, s74, s14
	v_lshl_add_u64 v[204:205], v[204:205], 0, s[66:67]
	s_mov_b32 m0, s0
	ds_read_b128 v[162:165], v241 offset:49152
	ds_read_b128 v[166:169], v241 offset:50176
	ds_read_b128 v[170:173], v241 offset:51200
	ds_read_b128 v[174:177], v241 offset:52224
	ds_read_b128 v[178:181], v241 offset:53248
	ds_read_b128 v[182:185], v241 offset:54272
	ds_read_b128 v[186:189], v241 offset:55296
	ds_read_b128 v[200:203], v241 offset:56320
	global_load_lds_dwordx4 v[204:205], off
	v_lshl_add_u64 v[204:205], v[206:207], 0, s[66:67]
	s_add_i32 m0, s0, 0x2000
	s_add_i32 s0, s75, s14
	global_load_lds_dwordx4 v[204:205], off
	v_lshl_add_u64 v[204:205], v[208:209], 0, s[66:67]
	s_mov_b32 m0, s0
	s_nop 0
	global_load_lds_dwordx4 v[204:205], off
	v_lshl_add_u64 v[204:205], v[210:211], 0, s[66:67]
	s_add_i32 m0, s0, 0x2000
	s_nop 0
	global_load_lds_dwordx4 v[204:205], off
	v_lshl_add_u64 v[204:205], v[212:213], 0, s[66:67]
	s_mov_b32 m0, s39
	s_nop 0
	global_load_lds_dwordx4 v[204:205], off
	v_lshl_add_u64 v[204:205], v[214:215], 0, s[66:67]
	s_mov_b32 m0, s40
	s_nop 0
	global_load_lds_dwordx4 v[204:205], off
	s_waitcnt vmcnt(8)
	s_waitcnt lgkmcnt(0)
	s_barrier
	v_mfma_f32_16x16x32_bf16 v[62:65], v[122:125], v[162:165], v[62:65]
	s_setprio 1
	v_mfma_f32_16x16x32_bf16 v[58:61], v[130:133], v[162:165], v[58:61]
	v_mfma_f32_16x16x32_bf16 v[50:53], v[122:125], v[170:173], v[50:53]
	v_mfma_f32_16x16x32_bf16 v[42:45], v[130:133], v[170:173], v[42:45]
	v_mfma_f32_16x16x32_bf16 v[34:37], v[122:125], v[178:181], v[34:37]
	v_mfma_f32_16x16x32_bf16 v[26:29], v[130:133], v[178:181], v[26:29]
	v_mfma_f32_16x16x32_bf16 v[18:21], v[122:125], v[186:189], v[18:21]
	v_mfma_f32_16x16x32_bf16 v[10:13], v[130:133], v[186:189], v[10:13]
	v_mfma_f32_16x16x32_bf16 v[62:65], v[126:129], v[166:169], v[62:65]
	v_mfma_f32_16x16x32_bf16 v[58:61], v[134:137], v[166:169], v[58:61]
	v_mfma_f32_16x16x32_bf16 v[50:53], v[126:129], v[174:177], v[50:53]
	v_mfma_f32_16x16x32_bf16 v[42:45], v[134:137], v[174:177], v[42:45]
	v_mfma_f32_16x16x32_bf16 v[34:37], v[126:129], v[182:185], v[34:37]
	v_mfma_f32_16x16x32_bf16 v[26:29], v[134:137], v[182:185], v[26:29]
	v_mfma_f32_16x16x32_bf16 v[18:21], v[126:129], v[200:203], v[18:21]
	v_mfma_f32_16x16x32_bf16 v[10:13], v[134:137], v[200:203], v[10:13]
	s_setprio 0
	s_setprio 1
	v_mfma_f32_16x16x32_bf16 v[54:57], v[138:141], v[162:165], v[54:57]
	v_mfma_f32_16x16x32_bf16 v[46:49], v[146:149], v[162:165], v[46:49]
	v_mfma_f32_16x16x32_bf16 v[38:41], v[138:141], v[170:173], v[38:41]
	v_mfma_f32_16x16x32_bf16 v[30:33], v[146:149], v[170:173], v[30:33]
	v_mfma_f32_16x16x32_bf16 v[22:25], v[138:141], v[178:181], v[22:25]
	v_mfma_f32_16x16x32_bf16 v[14:17], v[146:149], v[178:181], v[14:17]
	v_mfma_f32_16x16x32_bf16 v[6:9], v[138:141], v[186:189], v[6:9]
	v_mfma_f32_16x16x32_bf16 v[2:5], v[146:149], v[186:189], v[2:5]
	v_mfma_f32_16x16x32_bf16 v[54:57], v[142:145], v[166:169], v[54:57]
	v_mfma_f32_16x16x32_bf16 v[46:49], v[158:161], v[166:169], v[46:49]
	v_mfma_f32_16x16x32_bf16 v[38:41], v[142:145], v[174:177], v[38:41]
	v_mfma_f32_16x16x32_bf16 v[30:33], v[158:161], v[174:177], v[30:33]
	v_mfma_f32_16x16x32_bf16 v[22:25], v[142:145], v[182:185], v[22:25]
	v_mfma_f32_16x16x32_bf16 v[14:17], v[158:161], v[182:185], v[14:17]
	v_mfma_f32_16x16x32_bf16 v[6:9], v[142:145], v[200:203], v[6:9]
	v_mfma_f32_16x16x32_bf16 v[2:5], v[158:161], v[200:203], v[2:5]
	s_barrier
	s_setprio 0
	s_add_u32 s2, s2, 0x100
	s_addc_u32 s3, s3, 0
	s_add_u32 s65, s65, 0x100
	s_addc_u32 s68, s68, 0
	s_cmp_ge_u32 s69, s38
	s_mov_b32 s0, s69
	s_cbranch_scc0 .LBB0_647
	v_mov_b32_e32 v242, 0x9000
	v_mov_b32_e32 v244, 0x358637bd
	s_and_b64 vcc, exec, s[30:31]
	s_cbranch_vccz .LBB0_650
	s_barrier

.LBB0_669:
	s_add_i32 s53, s0, 2
	s_add_u32 s55, s2, 0x80
	s_addc_u32 s1, s3, 0
	s_add_i32 s68, 0, 0x10000
	s_cmp_eq_u32 s35, s0
	s_cselect_b32 s1, s7, s1
	s_cselect_b32 s0, s6, s55
	v_add_u32_e32 v140, s68, v143
	s_cselect_b32 s65, s23, s52
	s_cselect_b32 s64, s22, s43
	s_add_i32 s55, 0, 0x14000
	ds_read_b128 v[146:149], v140
	ds_read_b128 v[150:153], v140 offset:1024
	ds_read_b128 v[154:157], v140 offset:2048
	ds_read_b128 v[158:161], v140 offset:3072
	v_add_u32_e32 v140, s55, v143
	ds_read_b128 v[162:165], v140
	ds_read_b128 v[166:169], v140 offset:1024
	ds_read_b128 v[170:173], v140 offset:2048
	ds_read_b128 v[174:177], v140 offset:3072
	v_lshl_add_u64 v[140:141], s[2:3], 0, v[136:137]
	s_add_i32 m0, s26, 0xc000
	ds_read_b128 v[178:181], v145
	ds_read_b128 v[182:185], v145 offset:1024
	ds_read_b128 v[186:189], v145 offset:2048
	ds_read_b128 v[190:193], v145 offset:3072
	ds_read_b128 v[194:197], v145 offset:4096
	ds_read_b128 v[198:201], v145 offset:5120
	ds_read_b128 v[202:205], v145 offset:6144
	ds_read_b128 v[206:209], v145 offset:7168
	global_load_lds_dwordx4 v[140:141], off
	v_lshl_add_u64 v[140:141], s[2:3], 0, v[138:139]
	s_add_i32 m0, s26, 0xe000
	s_nop 0
	global_load_lds_dwordx4 v[140:141], off
	s_waitcnt vmcnt(8)
	s_waitcnt lgkmcnt(0)
	s_barrier
	v_mfma_f32_16x16x32_bf16 v[126:129], v[146:149], v[178:181], v[126:129]
	s_setprio 1
	v_mfma_f32_16x16x32_bf16 v[118:121], v[154:157], v[178:181], v[118:121]
	v_mfma_f32_16x16x32_bf16 v[110:113], v[146:149], v[186:189], v[110:113]
	v_mfma_f32_16x16x32_bf16 v[102:105], v[154:157], v[186:189], v[102:105]
	v_mfma_f32_16x16x32_bf16 v[94:97], v[146:149], v[194:197], v[94:97]
	v_mfma_f32_16x16x32_bf16 v[86:89], v[154:157], v[194:197], v[86:89]
	v_mfma_f32_16x16x32_bf16 v[78:81], v[146:149], v[202:205], v[78:81]
	v_mfma_f32_16x16x32_bf16 v[70:73], v[154:157], v[202:205], v[70:73]
	v_mfma_f32_16x16x32_bf16 v[126:129], v[150:153], v[182:185], v[126:129]
	v_mfma_f32_16x16x32_bf16 v[118:121], v[158:161], v[182:185], v[118:121]
	v_mfma_f32_16x16x32_bf16 v[110:113], v[150:153], v[190:193], v[110:113]
	v_mfma_f32_16x16x32_bf16 v[102:105], v[158:161], v[190:193], v[102:105]
	v_mfma_f32_16x16x32_bf16 v[94:97], v[150:153], v[198:201], v[94:97]
	v_mfma_f32_16x16x32_bf16 v[86:89], v[158:161], v[198:201], v[86:89]
	v_mfma_f32_16x16x32_bf16 v[78:81], v[150:153], v[206:209], v[78:81]
	v_mfma_f32_16x16x32_bf16 v[70:73], v[158:161], v[206:209], v[70:73]
	s_setprio 0
	s_setprio 1
	v_mfma_f32_16x16x32_bf16 v[122:125], v[162:165], v[178:181], v[122:125]
	v_mfma_f32_16x16x32_bf16 v[114:117], v[170:173], v[178:181], v[114:117]
	v_mfma_f32_16x16x32_bf16 v[106:109], v[162:165], v[186:189], v[106:109]
	v_mfma_f32_16x16x32_bf16 v[98:101], v[170:173], v[186:189], v[98:101]
	v_mfma_f32_16x16x32_bf16 v[90:93], v[162:165], v[194:197], v[90:93]
	v_mfma_f32_16x16x32_bf16 v[82:85], v[170:173], v[194:197], v[82:85]
	v_mfma_f32_16x16x32_bf16 v[74:77], v[162:165], v[202:205], v[74:77]
	v_mfma_f32_16x16x32_bf16 v[66:69], v[170:173], v[202:205], v[66:69]
	v_mfma_f32_16x16x32_bf16 v[122:125], v[166:169], v[182:185], v[122:125]
	v_mfma_f32_16x16x32_bf16 v[114:117], v[174:177], v[182:185], v[114:117]
	v_mfma_f32_16x16x32_bf16 v[106:109], v[166:169], v[190:193], v[106:109]
	v_mfma_f32_16x16x32_bf16 v[98:101], v[174:177], v[190:193], v[98:101]
	v_mfma_f32_16x16x32_bf16 v[90:93], v[166:169], v[198:201], v[90:93]
	v_mfma_f32_16x16x32_bf16 v[82:85], v[174:177], v[198:201], v[82:85]
	v_mfma_f32_16x16x32_bf16 v[74:77], v[166:169], v[206:209], v[74:77]
	v_mfma_f32_16x16x32_bf16 v[66:69], v[174:177], v[206:209], v[66:69]
	s_barrier
	s_setprio 0
	s_add_i32 s68, s68, s14
	v_lshl_add_u64 v[140:141], s[64:65], 0, v[0:1]
	s_mov_b32 m0, s68
	ds_read_b128 v[178:181], v145 offset:16384
	ds_read_b128 v[182:185], v145 offset:17408
	ds_read_b128 v[186:189], v145 offset:18432
	ds_read_b128 v[190:193], v145 offset:19456
	ds_read_b128 v[194:197], v145 offset:20480
	ds_read_b128 v[198:201], v145 offset:21504
	ds_read_b128 v[202:205], v145 offset:22528
	ds_read_b128 v[206:209], v145 offset:23552
	global_load_lds_dwordx4 v[140:141], off
	s_add_i32 m0, s68, 0x2000
	v_lshl_add_u64 v[210:211], s[64:65], 0, v[130:131]
	s_add_u32 s64, s64, s50
	s_addc_u32 s65, s65, 0
	s_add_i32 s55, s55, s14
	global_load_lds_dwordx4 v[210:211], off
	v_lshl_add_u64 v[212:213], s[64:65], 0, v[0:1]
	s_mov_b32 m0, s55
	v_lshl_add_u64 v[214:215], s[64:65], 0, v[130:131]
	global_load_lds_dwordx4 v[212:213], off
	s_add_i32 m0, s55, 0x2000
	v_lshl_add_u64 v[216:217], s[0:1], 0, v[134:135]
	global_load_lds_dwordx4 v[214:215], off
	s_mov_b32 m0, s26
	v_lshl_add_u64 v[218:219], s[0:1], 0, v[132:133]
	global_load_lds_dwordx4 v[216:217], off
	s_mov_b32 m0, s27
	s_nop 0
	global_load_lds_dwordx4 v[218:219], off
	s_waitcnt vmcnt(8)
	s_waitcnt lgkmcnt(0)
	s_barrier
	v_mfma_f32_16x16x32_bf16 v[62:65], v[146:149], v[178:181], v[62:65]
	s_setprio 1
	v_mfma_f32_16x16x32_bf16 v[54:57], v[154:157], v[178:181], v[54:57]
	v_mfma_f32_16x16x32_bf16 v[46:49], v[146:149], v[186:189], v[46:49]
	v_mfma_f32_16x16x32_bf16 v[38:41], v[154:157], v[186:189], v[38:41]
	v_mfma_f32_16x16x32_bf16 v[30:33], v[146:149], v[194:197], v[30:33]
	v_mfma_f32_16x16x32_bf16 v[22:25], v[154:157], v[194:197], v[22:25]
	v_mfma_f32_16x16x32_bf16 v[14:17], v[146:149], v[202:205], v[14:17]
	v_mfma_f32_16x16x32_bf16 v[6:9], v[154:157], v[202:205], v[6:9]
	v_mfma_f32_16x16x32_bf16 v[62:65], v[150:153], v[182:185], v[62:65]
	v_mfma_f32_16x16x32_bf16 v[54:57], v[158:161], v[182:185], v[54:57]
	v_mfma_f32_16x16x32_bf16 v[46:49], v[150:153], v[190:193], v[46:49]
	v_mfma_f32_16x16x32_bf16 v[38:41], v[158:161], v[190:193], v[38:41]
	v_mfma_f32_16x16x32_bf16 v[30:33], v[150:153], v[198:201], v[30:33]
	v_mfma_f32_16x16x32_bf16 v[22:25], v[158:161], v[198:201], v[22:25]
	v_mfma_f32_16x16x32_bf16 v[14:17], v[150:153], v[206:209], v[14:17]
	v_mfma_f32_16x16x32_bf16 v[6:9], v[158:161], v[206:209], v[6:9]
	s_setprio 0
	s_setprio 1
	v_mfma_f32_16x16x32_bf16 v[58:61], v[162:165], v[178:181], v[58:61]
	v_mfma_f32_16x16x32_bf16 v[50:53], v[170:173], v[178:181], v[50:53]
	v_mfma_f32_16x16x32_bf16 v[42:45], v[162:165], v[186:189], v[42:45]
	v_mfma_f32_16x16x32_bf16 v[34:37], v[170:173], v[186:189], v[34:37]
	v_mfma_f32_16x16x32_bf16 v[26:29], v[162:165], v[194:197], v[26:29]
	v_mfma_f32_16x16x32_bf16 v[18:21], v[170:173], v[194:197], v[18:21]
	v_mfma_f32_16x16x32_bf16 v[10:13], v[162:165], v[202:205], v[10:13]
	v_mfma_f32_16x16x32_bf16 v[2:5], v[170:173], v[202:205], v[2:5]
	v_mfma_f32_16x16x32_bf16 v[58:61], v[166:169], v[182:185], v[58:61]
	v_mfma_f32_16x16x32_bf16 v[50:53], v[174:177], v[182:185], v[50:53]
	v_mfma_f32_16x16x32_bf16 v[42:45], v[166:169], v[190:193], v[42:45]
	v_mfma_f32_16x16x32_bf16 v[34:37], v[174:177], v[190:193], v[34:37]
	v_mfma_f32_16x16x32_bf16 v[26:29], v[166:169], v[198:201], v[26:29]
	v_mfma_f32_16x16x32_bf16 v[18:21], v[174:177], v[198:201], v[18:21]
	v_mfma_f32_16x16x32_bf16 v[10:13], v[166:169], v[206:209], v[10:13]
	v_mfma_f32_16x16x32_bf16 v[2:5], v[174:177], v[206:209], v[2:5]
	s_barrier
	s_setprio 0
	s_add_i32 s55, 0, 0x18000
	s_add_i32 s64, 0, 0x1c000
	v_add_u32_e32 v158, s55, v143
	v_add_u32_e32 v174, s64, v143
	ds_read_b128 v[146:149], v158
	ds_read_b128 v[150:153], v158 offset:1024
	ds_read_b128 v[154:157], v158 offset:2048
	ds_read_b128 v[158:161], v158 offset:3072
	ds_read_b128 v[162:165], v174
	ds_read_b128 v[166:169], v174 offset:1024
	ds_read_b128 v[170:173], v174 offset:2048
	ds_read_b128 v[174:177], v174 offset:3072
	s_add_u32 s0, s0, s50
	s_addc_u32 s1, s1, 0
	s_mov_b32 m0, s28
	v_lshl_add_u64 v[220:221], s[0:1], 0, v[134:135]
	ds_read_b128 v[178:181], v145 offset:32768
	ds_read_b128 v[182:185], v145 offset:33792
	ds_read_b128 v[186:189], v145 offset:34816
	ds_read_b128 v[190:193], v145 offset:35840
	ds_read_b128 v[194:197], v145 offset:36864
	ds_read_b128 v[198:201], v145 offset:37888
	ds_read_b128 v[202:205], v145 offset:38912
	ds_read_b128 v[206:209], v145 offset:39936
	global_load_lds_dwordx4 v[220:221], off
	v_lshl_add_u64 v[220:221], s[0:1], 0, v[132:133]
	s_mov_b32 m0, s29
	s_nop 0
	global_load_lds_dwordx4 v[220:221], off
	s_waitcnt vmcnt(8)
	s_waitcnt lgkmcnt(0)
	s_barrier
	v_mfma_f32_16x16x32_bf16 v[126:129], v[146:149], v[178:181], v[126:129]
	s_setprio 1
	v_mfma_f32_16x16x32_bf16 v[118:121], v[154:157], v[178:181], v[118:121]
	v_mfma_f32_16x16x32_bf16 v[110:113], v[146:149], v[186:189], v[110:113]
	v_mfma_f32_16x16x32_bf16 v[102:105], v[154:157], v[186:189], v[102:105]
	v_mfma_f32_16x16x32_bf16 v[94:97], v[146:149], v[194:197], v[94:97]
	v_mfma_f32_16x16x32_bf16 v[86:89], v[154:157], v[194:197], v[86:89]
	v_mfma_f32_16x16x32_bf16 v[78:81], v[146:149], v[202:205], v[78:81]
	v_mfma_f32_16x16x32_bf16 v[70:73], v[154:157], v[202:205], v[70:73]
	v_mfma_f32_16x16x32_bf16 v[126:129], v[150:153], v[182:185], v[126:129]
	v_mfma_f32_16x16x32_bf16 v[118:121], v[158:161], v[182:185], v[118:121]
	v_mfma_f32_16x16x32_bf16 v[110:113], v[150:153], v[190:193], v[110:113]
	v_mfma_f32_16x16x32_bf16 v[102:105], v[158:161], v[190:193], v[102:105]
	v_mfma_f32_16x16x32_bf16 v[94:97], v[150:153], v[198:201], v[94:97]
	v_mfma_f32_16x16x32_bf16 v[86:89], v[158:161], v[198:201], v[86:89]
	v_mfma_f32_16x16x32_bf16 v[78:81], v[150:153], v[206:209], v[78:81]
	v_mfma_f32_16x16x32_bf16 v[70:73], v[158:161], v[206:209], v[70:73]
	s_setprio 0
	s_setprio 1
	v_mfma_f32_16x16x32_bf16 v[122:125], v[162:165], v[178:181], v[122:125]
	v_mfma_f32_16x16x32_bf16 v[114:117], v[170:173], v[178:181], v[114:117]
	v_mfma_f32_16x16x32_bf16 v[106:109], v[162:165], v[186:189], v[106:109]
	v_mfma_f32_16x16x32_bf16 v[98:101], v[170:173], v[186:189], v[98:101]
	v_mfma_f32_16x16x32_bf16 v[90:93], v[162:165], v[194:197], v[90:93]
	v_mfma_f32_16x16x32_bf16 v[82:85], v[170:173], v[194:197], v[82:85]
	v_mfma_f32_16x16x32_bf16 v[74:77], v[162:165], v[202:205], v[74:77]
	v_mfma_f32_16x16x32_bf16 v[66:69], v[170:173], v[202:205], v[66:69]
	v_mfma_f32_16x16x32_bf16 v[122:125], v[166:169], v[182:185], v[122:125]
	v_mfma_f32_16x16x32_bf16 v[114:117], v[174:177], v[182:185], v[114:117]
	v_mfma_f32_16x16x32_bf16 v[106:109], v[166:169], v[190:193], v[106:109]
	v_mfma_f32_16x16x32_bf16 v[98:101], v[174:177], v[190:193], v[98:101]
	v_mfma_f32_16x16x32_bf16 v[90:93], v[166:169], v[198:201], v[90:93]
	v_mfma_f32_16x16x32_bf16 v[82:85], v[174:177], v[198:201], v[82:85]
	v_mfma_f32_16x16x32_bf16 v[74:77], v[166:169], v[206:209], v[74:77]
	v_mfma_f32_16x16x32_bf16 v[66:69], v[174:177], v[206:209], v[66:69]
	s_barrier
	s_setprio 0
	s_add_i32 s0, s55, s14
	v_lshl_add_u64 v[140:141], v[140:141], 0, s[66:67]
	s_mov_b32 m0, s0
	ds_read_b128 v[178:181], v145 offset:49152
	ds_read_b128 v[182:185], v145 offset:50176
	ds_read_b128 v[186:189], v145 offset:51200
	ds_read_b128 v[190:193], v145 offset:52224
	ds_read_b128 v[194:197], v145 offset:53248
	ds_read_b128 v[198:201], v145 offset:54272
	ds_read_b128 v[202:205], v145 offset:55296
	ds_read_b128 v[206:209], v145 offset:56320
	global_load_lds_dwordx4 v[140:141], off
	v_lshl_add_u64 v[140:141], v[210:211], 0, s[66:67]
	s_add_i32 m0, s0, 0x2000
	s_add_i32 s0, s64, s14
	global_load_lds_dwordx4 v[140:141], off
	v_lshl_add_u64 v[140:141], v[212:213], 0, s[66:67]
	s_mov_b32 m0, s0
	s_nop 0
	global_load_lds_dwordx4 v[140:141], off
	v_lshl_add_u64 v[140:141], v[214:215], 0, s[66:67]
	s_add_i32 m0, s0, 0x2000
	s_nop 0
	global_load_lds_dwordx4 v[140:141], off
	v_lshl_add_u64 v[140:141], v[216:217], 0, s[66:67]
	s_mov_b32 m0, s30
	s_nop 0
	global_load_lds_dwordx4 v[140:141], off
	v_lshl_add_u64 v[140:141], v[218:219], 0, s[66:67]
	s_mov_b32 m0, s31
	s_nop 0
	global_load_lds_dwordx4 v[140:141], off
	s_waitcnt vmcnt(8)
	s_waitcnt lgkmcnt(0)
	s_barrier
	v_mfma_f32_16x16x32_bf16 v[62:65], v[146:149], v[178:181], v[62:65]
	s_setprio 1
	v_mfma_f32_16x16x32_bf16 v[54:57], v[154:157], v[178:181], v[54:57]
	v_mfma_f32_16x16x32_bf16 v[46:49], v[146:149], v[186:189], v[46:49]
	v_mfma_f32_16x16x32_bf16 v[38:41], v[154:157], v[186:189], v[38:41]
	v_mfma_f32_16x16x32_bf16 v[30:33], v[146:149], v[194:197], v[30:33]
	v_mfma_f32_16x16x32_bf16 v[22:25], v[154:157], v[194:197], v[22:25]
	v_mfma_f32_16x16x32_bf16 v[14:17], v[146:149], v[202:205], v[14:17]
	v_mfma_f32_16x16x32_bf16 v[6:9], v[154:157], v[202:205], v[6:9]
	v_mfma_f32_16x16x32_bf16 v[62:65], v[150:153], v[182:185], v[62:65]
	v_mfma_f32_16x16x32_bf16 v[54:57], v[158:161], v[182:185], v[54:57]
	v_mfma_f32_16x16x32_bf16 v[46:49], v[150:153], v[190:193], v[46:49]
	v_mfma_f32_16x16x32_bf16 v[38:41], v[158:161], v[190:193], v[38:41]
	v_mfma_f32_16x16x32_bf16 v[30:33], v[150:153], v[198:201], v[30:33]
	v_mfma_f32_16x16x32_bf16 v[22:25], v[158:161], v[198:201], v[22:25]
	v_mfma_f32_16x16x32_bf16 v[14:17], v[150:153], v[206:209], v[14:17]
	v_mfma_f32_16x16x32_bf16 v[6:9], v[158:161], v[206:209], v[6:9]
	s_setprio 0
	s_setprio 1
	v_mfma_f32_16x16x32_bf16 v[58:61], v[162:165], v[178:181], v[58:61]
	v_mfma_f32_16x16x32_bf16 v[50:53], v[170:173], v[178:181], v[50:53]
	v_mfma_f32_16x16x32_bf16 v[42:45], v[162:165], v[186:189], v[42:45]
	v_mfma_f32_16x16x32_bf16 v[34:37], v[170:173], v[186:189], v[34:37]
	v_mfma_f32_16x16x32_bf16 v[26:29], v[162:165], v[194:197], v[26:29]
	v_mfma_f32_16x16x32_bf16 v[18:21], v[170:173], v[194:197], v[18:21]
	v_mfma_f32_16x16x32_bf16 v[10:13], v[162:165], v[202:205], v[10:13]
	v_mfma_f32_16x16x32_bf16 v[2:5], v[170:173], v[202:205], v[2:5]
	v_mfma_f32_16x16x32_bf16 v[58:61], v[166:169], v[182:185], v[58:61]
	v_mfma_f32_16x16x32_bf16 v[50:53], v[174:177], v[182:185], v[50:53]
	v_mfma_f32_16x16x32_bf16 v[42:45], v[166:169], v[190:193], v[42:45]
	v_mfma_f32_16x16x32_bf16 v[34:37], v[174:177], v[190:193], v[34:37]
	v_mfma_f32_16x16x32_bf16 v[26:29], v[166:169], v[198:201], v[26:29]
	v_mfma_f32_16x16x32_bf16 v[18:21], v[174:177], v[198:201], v[18:21]
	v_mfma_f32_16x16x32_bf16 v[10:13], v[166:169], v[206:209], v[10:13]
	v_mfma_f32_16x16x32_bf16 v[2:5], v[174:177], v[206:209], v[2:5]
	s_barrier
	s_setprio 0
	s_add_u32 s2, s2, 0x100
	s_addc_u32 s3, s3, 0
	s_add_u32 s43, s43, 0x100
	s_addc_u32 s52, s52, 0
	s_cmp_ge_u32 s53, s34
	s_mov_b32 s0, s53
	s_cbranch_scc0 .LBB0_669
	s_and_b64 vcc, exec, s[20:21]
	s_cbranch_vccz .LBB0_672
	s_barrier
